# v22 + packed-f32 VALU in the SwiGLU epilogue + full-line bf16 stores in the proj GEMM epilogue
# speedup vs baseline: 1.0183x; 1.0084x over previous
;     ...
;   __syncthreads();
;   G2_STAGE(0); G2_STAGE(1);
;   const int fsw = (0x78 >> (((r16 >> 2) & 3) * 2)) & 3;
;   const int aoff = (wm * 128 + r16) * 64 + ((quad ^ fsw) << 4);
;   const int boff = 16384 + (wn * 64 + r16) * 64 + ((quad ^ fsw) << 4);
;   for (int kt = 0; kt < nk; kt++) {
;     if (kt + 1 < nk) asm volatile("s_waitcnt vmcnt(6)" ::: "memory");
;     else asm volatile("s_waitcnt vmcnt(0)" ::: "memory");
;     __builtin_amdgcn_s_barrier();
;     asm volatile("" ::: "memory");
;     if (kt + 2 < nk) G2_STAGE(kt + 2);
;     const char* cS = smem + (kt % 3) * 24576;
;     bf16x8 xa[8], wb[4];
; #pragma unroll
;     for (int f = 0; f < 8; f++) xa[f] = *(const bf16x8*)(cS + aoff + f * 1024);
; #pragma unroll
;     for (int f = 0; f < 4; f++) wb[f] = *(const bf16x8*)(cS + boff + f * 1024);
; #pragma unroll
;     for (int nf = 0; nf < 4; nf++)
; #pragma unroll
;       for (int mf = 0; mf < 8; mf++)
;         acc[nf][mf] = __builtin_amdgcn_mfma_f32_16x16x32_bf16(wb[nf], xa[mf], acc[nf][mf], 0, 0, 0);
;   }
.Lt10_loop:
	.p2align 3
	s_waitcnt vmcnt(6) lgkmcnt(0)
	s_barrier
	s_setprio 1
	v_add_u32_e32 v144, s36, v136
	v_mfma_f32_16x16x32_bf16 v[126:129], v[184:187], v[146:149], v[126:129]
	ds_read_b128 v[200:203], v144 offset:0
	v_mfma_f32_16x16x32_bf16 v[122:125], v[184:187], v[152:155], v[122:125]
	ds_read_b128 v[204:207], v144 offset:1024
	v_mfma_f32_16x16x32_bf16 v[118:121], v[184:187], v[156:159], v[118:121]
	ds_read_b128 v[208:211], v144 offset:2048
	v_mfma_f32_16x16x32_bf16 v[114:117], v[184:187], v[162:165], v[114:117]
	ds_read_b128 v[212:215], v144 offset:3072
	v_mfma_f32_16x16x32_bf16 v[110:113], v[184:187], v[166:169], v[110:113]
	ds_read_b128 v[216:219], v144 offset:4096
	v_mfma_f32_16x16x32_bf16 v[106:109], v[184:187], v[170:173], v[106:109]
	ds_read_b128 v[220:223], v144 offset:5120
	v_mfma_f32_16x16x32_bf16 v[102:105], v[184:187], v[176:179], v[102:105]
	ds_read_b128 v[224:227], v144 offset:6144
	v_mfma_f32_16x16x32_bf16 v[98:101], v[184:187], v[180:183], v[98:101]
	ds_read_b128 v[228:231], v144 offset:7168
	v_mfma_f32_16x16x32_bf16 v[94:97], v[188:191], v[146:149], v[94:97]
	v_add_u32_e64 v144, s36, v137
	v_mfma_f32_16x16x32_bf16 v[90:93], v[188:191], v[152:155], v[90:93]
	v_mfma_f32_16x16x32_bf16 v[86:89], v[188:191], v[156:159], v[86:89]
	ds_read_b128 v[232:235], v144 offset:16384
	v_mfma_f32_16x16x32_bf16 v[82:85], v[188:191], v[162:165], v[82:85]
	ds_read_b128 v[236:239], v144 offset:17408
	v_mfma_f32_16x16x32_bf16 v[78:81], v[188:191], v[166:169], v[78:81]
	ds_read_b128 v[240:243], v144 offset:18432
	v_mfma_f32_16x16x32_bf16 v[74:77], v[188:191], v[170:173], v[74:77]
	ds_read_b128 v[244:247], v144 offset:19456
	v_mfma_f32_16x16x32_bf16 v[70:73], v[188:191], v[176:179], v[70:73]
	s_add_i32 s38, s43, s37
	s_mov_b32 m0, s38
	v_lshl_add_u64 v[142:143], v[132:133], 0, s[2:3]
	v_mfma_f32_16x16x32_bf16 v[66:69], v[188:191], v[180:183], v[66:69]
	global_load_lds_dwordx4 v[132:133], off
	s_add_i32 m0, m0, 0x1000
	v_mfma_f32_16x16x32_bf16 v[62:65], v[192:195], v[146:149], v[62:65]
	v_mfma_f32_16x16x32_bf16 v[58:61], v[192:195], v[152:155], v[58:61]
	v_mfma_f32_16x16x32_bf16 v[54:57], v[192:195], v[156:159], v[54:57]
	global_load_lds_dwordx4 v[142:143], off
	v_lshl_add_u64 v[142:143], v[142:143], 0, s[2:3]
	s_add_i32 m0, m0, 0x1000
	v_mfma_f32_16x16x32_bf16 v[50:53], v[192:195], v[162:165], v[50:53]
	v_mfma_f32_16x16x32_bf16 v[46:49], v[192:195], v[166:169], v[46:49]
	v_mfma_f32_16x16x32_bf16 v[42:45], v[192:195], v[170:173], v[42:45]
	global_load_lds_dwordx4 v[142:143], off
	v_lshl_add_u64 v[142:143], v[142:143], 0, s[2:3]
	s_add_i32 m0, m0, 0x1000
	v_mfma_f32_16x16x32_bf16 v[38:41], v[192:195], v[176:179], v[38:41]
	v_mfma_f32_16x16x32_bf16 v[34:37], v[192:195], v[180:183], v[34:37]
	v_mfma_f32_16x16x32_bf16 v[30:33], v[196:199], v[146:149], v[30:33]
	global_load_lds_dwordx4 v[142:143], off
	s_add_i32 m0, m0, 0x1000
	v_lshl_add_u64 v[142:143], v[134:135], 0, s[2:3]
	v_mfma_f32_16x16x32_bf16 v[26:29], v[196:199], v[152:155], v[26:29]
	v_mfma_f32_16x16x32_bf16 v[22:25], v[196:199], v[156:159], v[22:25]
	v_mfma_f32_16x16x32_bf16 v[18:21], v[196:199], v[162:165], v[18:21]
	global_load_lds_dwordx4 v[134:135], off
	s_add_i32 m0, m0, 0x1000
	v_lshl_add_u64 v[132:133], v[132:133], 0, s[14:15]
	v_mfma_f32_16x16x32_bf16 v[14:17], v[196:199], v[166:169], v[14:17]
	v_mfma_f32_16x16x32_bf16 v[10:13], v[196:199], v[170:173], v[10:13]
	v_mfma_f32_16x16x32_bf16 v[6:9], v[196:199], v[176:179], v[6:9]
	global_load_lds_dwordx4 v[142:143], off
	v_lshl_add_u64 v[134:135], v[134:135], 0, s[10:11]
	v_mfma_f32_16x16x32_bf16 v[2:5], v[196:199], v[180:183], v[2:5]
	s_setprio 0
	s_mov_b32 s37, s36
	s_add_i32 s36, s36, 0x6000
	s_cmp_eq_u32 s36, 0x12000
	s_cselect_b32 s36, 0, s36
	s_nop 0
	.p2align 3
	s_waitcnt vmcnt(6) lgkmcnt(0)
	s_barrier
	s_setprio 1
	v_add_u32_e32 v144, s36, v136
	v_mfma_f32_16x16x32_bf16 v[126:129], v[232:235], v[200:203], v[126:129]
	ds_read_b128 v[146:149], v144 offset:0
	v_mfma_f32_16x16x32_bf16 v[122:125], v[232:235], v[204:207], v[122:125]
	ds_read_b128 v[152:155], v144 offset:1024
	v_mfma_f32_16x16x32_bf16 v[118:121], v[232:235], v[208:211], v[118:121]
	ds_read_b128 v[156:159], v144 offset:2048
	v_mfma_f32_16x16x32_bf16 v[114:117], v[232:235], v[212:215], v[114:117]
	ds_read_b128 v[162:165], v144 offset:3072
	v_mfma_f32_16x16x32_bf16 v[110:113], v[232:235], v[216:219], v[110:113]
	ds_read_b128 v[166:169], v144 offset:4096
	v_mfma_f32_16x16x32_bf16 v[106:109], v[232:235], v[220:223], v[106:109]
	ds_read_b128 v[170:173], v144 offset:5120
	v_mfma_f32_16x16x32_bf16 v[102:105], v[232:235], v[224:227], v[102:105]
	ds_read_b128 v[176:179], v144 offset:6144
	v_mfma_f32_16x16x32_bf16 v[98:101], v[232:235], v[228:231], v[98:101]
	ds_read_b128 v[180:183], v144 offset:7168
	v_mfma_f32_16x16x32_bf16 v[94:97], v[236:239], v[200:203], v[94:97]
	v_add_u32_e64 v144, s36, v137
	v_mfma_f32_16x16x32_bf16 v[90:93], v[236:239], v[204:207], v[90:93]
	v_mfma_f32_16x16x32_bf16 v[86:89], v[236:239], v[208:211], v[86:89]
	ds_read_b128 v[184:187], v144 offset:16384
	v_mfma_f32_16x16x32_bf16 v[82:85], v[236:239], v[212:215], v[82:85]
	ds_read_b128 v[188:191], v144 offset:17408
	v_mfma_f32_16x16x32_bf16 v[78:81], v[236:239], v[216:219], v[78:81]
	ds_read_b128 v[192:195], v144 offset:18432
	v_mfma_f32_16x16x32_bf16 v[74:77], v[236:239], v[220:223], v[74:77]
	ds_read_b128 v[196:199], v144 offset:19456
	v_mfma_f32_16x16x32_bf16 v[70:73], v[236:239], v[224:227], v[70:73]
	s_add_i32 s38, s43, s37
	s_mov_b32 m0, s38
	v_lshl_add_u64 v[142:143], v[132:133], 0, s[2:3]
	v_mfma_f32_16x16x32_bf16 v[66:69], v[236:239], v[228:231], v[66:69]
	global_load_lds_dwordx4 v[132:133], off
;     ...
;   __syncthreads();
;   G2_STAGE(0); G2_STAGE(1);
;   const int fsw = (0x78 >> (((r16 >> 2) & 3) * 2)) & 3;
;   const int aoff = (wm * 128 + r16) * 64 + ((quad ^ fsw) << 4);
;   const int boff = 16384 + (wn * 64 + r16) * 64 + ((quad ^ fsw) << 4);
;   for (int kt = 0; kt < nk; kt++) {
;     if (kt + 1 < nk) asm volatile("s_waitcnt vmcnt(6)" ::: "memory");
;     else asm volatile("s_waitcnt vmcnt(0)" ::: "memory");
;     __builtin_amdgcn_s_barrier();
;     asm volatile("" ::: "memory");
;     if (kt + 2 < nk) G2_STAGE(kt + 2);
;     const char* cS = smem + (kt % 3) * 24576;
;     bf16x8 xa[8], wb[4];
; #pragma unroll
;     for (int f = 0; f < 8; f++) xa[f] = *(const bf16x8*)(cS + aoff + f * 1024);
; #pragma unroll
;     for (int f = 0; f < 4; f++) wb[f] = *(const bf16x8*)(cS + boff + f * 1024);
; #pragma unroll
;     for (int nf = 0; nf < 4; nf++)
; #pragma unroll
;       for (int mf = 0; mf < 8; mf++)
;         acc[nf][mf] = __builtin_amdgcn_mfma_f32_16x16x32_bf16(wb[nf], xa[mf], acc[nf][mf], 0, 0, 0);
;   }
	s_add_i32 m0, m0, 0x1000
	v_mfma_f32_16x16x32_bf16 v[62:65], v[240:243], v[200:203], v[62:65]
	v_mfma_f32_16x16x32_bf16 v[58:61], v[240:243], v[204:207], v[58:61]
	v_mfma_f32_16x16x32_bf16 v[54:57], v[240:243], v[208:211], v[54:57]
	global_load_lds_dwordx4 v[142:143], off
	v_lshl_add_u64 v[142:143], v[142:143], 0, s[2:3]
	s_add_i32 m0, m0, 0x1000
	v_mfma_f32_16x16x32_bf16 v[50:53], v[240:243], v[212:215], v[50:53]
	v_mfma_f32_16x16x32_bf16 v[46:49], v[240:243], v[216:219], v[46:49]
	v_mfma_f32_16x16x32_bf16 v[42:45], v[240:243], v[220:223], v[42:45]
	global_load_lds_dwordx4 v[142:143], off
	v_lshl_add_u64 v[142:143], v[142:143], 0, s[2:3]
	s_add_i32 m0, m0, 0x1000
	v_mfma_f32_16x16x32_bf16 v[38:41], v[240:243], v[224:227], v[38:41]
	v_mfma_f32_16x16x32_bf16 v[34:37], v[240:243], v[228:231], v[34:37]
	v_mfma_f32_16x16x32_bf16 v[30:33], v[244:247], v[200:203], v[30:33]
	global_load_lds_dwordx4 v[142:143], off
	s_add_i32 m0, m0, 0x1000
	v_lshl_add_u64 v[142:143], v[134:135], 0, s[2:3]
	v_mfma_f32_16x16x32_bf16 v[26:29], v[244:247], v[204:207], v[26:29]
	v_mfma_f32_16x16x32_bf16 v[22:25], v[244:247], v[208:211], v[22:25]
	v_mfma_f32_16x16x32_bf16 v[18:21], v[244:247], v[212:215], v[18:21]
	global_load_lds_dwordx4 v[134:135], off
	s_add_i32 m0, m0, 0x1000
	v_lshl_add_u64 v[132:133], v[132:133], 0, s[14:15]
	v_mfma_f32_16x16x32_bf16 v[14:17], v[244:247], v[216:219], v[14:17]
	v_mfma_f32_16x16x32_bf16 v[10:13], v[244:247], v[220:223], v[10:13]
	v_mfma_f32_16x16x32_bf16 v[6:9], v[244:247], v[224:227], v[6:9]
	global_load_lds_dwordx4 v[142:143], off
	v_lshl_add_u64 v[134:135], v[134:135], 0, s[10:11]
	v_mfma_f32_16x16x32_bf16 v[2:5], v[244:247], v[228:231], v[2:5]
	s_setprio 0
	s_mov_b32 s37, s36
	s_add_i32 s36, s36, 0x6000
	s_cmp_eq_u32 s36, 0x12000
	s_cselect_b32 s36, 0, s36
	s_nop 0
	s_sub_i32 s9, s9, 1
	s_cmp_lg_u32 s9, 0
	s_cbranch_scc1 .Lt10_loop
	.p2align 3
	s_waitcnt vmcnt(6) lgkmcnt(0)
	s_barrier
	s_setprio 1
	v_add_u32_e32 v144, s36, v136
	v_mfma_f32_16x16x32_bf16 v[126:129], v[184:187], v[146:149], v[126:129]
	ds_read_b128 v[200:203], v144 offset:0
	v_mfma_f32_16x16x32_bf16 v[122:125], v[184:187], v[152:155], v[122:125]
	ds_read_b128 v[204:207], v144 offset:1024
	v_mfma_f32_16x16x32_bf16 v[118:121], v[184:187], v[156:159], v[118:121]
	ds_read_b128 v[208:211], v144 offset:2048
	v_mfma_f32_16x16x32_bf16 v[114:117], v[184:187], v[162:165], v[114:117]
	ds_read_b128 v[212:215], v144 offset:3072
	v_mfma_f32_16x16x32_bf16 v[110:113], v[184:187], v[166:169], v[110:113]
	ds_read_b128 v[216:219], v144 offset:4096
	v_mfma_f32_16x16x32_bf16 v[106:109], v[184:187], v[170:173], v[106:109]
	ds_read_b128 v[220:223], v144 offset:5120
	v_mfma_f32_16x16x32_bf16 v[102:105], v[184:187], v[176:179], v[102:105]
	ds_read_b128 v[224:227], v144 offset:6144
	v_mfma_f32_16x16x32_bf16 v[98:101], v[184:187], v[180:183], v[98:101]
	ds_read_b128 v[228:231], v144 offset:7168
	v_mfma_f32_16x16x32_bf16 v[94:97], v[188:191], v[146:149], v[94:97]
	v_add_u32_e64 v144, s36, v137
	v_mfma_f32_16x16x32_bf16 v[90:93], v[188:191], v[152:155], v[90:93]
	v_mfma_f32_16x16x32_bf16 v[86:89], v[188:191], v[156:159], v[86:89]
	ds_read_b128 v[232:235], v144 offset:16384
	v_mfma_f32_16x16x32_bf16 v[82:85], v[188:191], v[162:165], v[82:85]
	ds_read_b128 v[236:239], v144 offset:17408
	v_mfma_f32_16x16x32_bf16 v[78:81], v[188:191], v[166:169], v[78:81]
	ds_read_b128 v[240:243], v144 offset:18432
	v_mfma_f32_16x16x32_bf16 v[74:77], v[188:191], v[170:173], v[74:77]
	ds_read_b128 v[244:247], v144 offset:19456
	v_mfma_f32_16x16x32_bf16 v[70:73], v[188:191], v[176:179], v[70:73]
	s_add_i32 s38, s43, s37
	s_mov_b32 m0, s38
	v_lshl_add_u64 v[142:143], v[132:133], 0, s[2:3]
	v_mfma_f32_16x16x32_bf16 v[66:69], v[188:191], v[180:183], v[66:69]
	global_load_lds_dwordx4 v[132:133], off
	s_add_i32 m0, m0, 0x1000
	v_mfma_f32_16x16x32_bf16 v[62:65], v[192:195], v[146:149], v[62:65]
	v_mfma_f32_16x16x32_bf16 v[58:61], v[192:195], v[152:155], v[58:61]
	v_mfma_f32_16x16x32_bf16 v[54:57], v[192:195], v[156:159], v[54:57]
	global_load_lds_dwordx4 v[142:143], off
	v_lshl_add_u64 v[142:143], v[142:143], 0, s[2:3]
	s_add_i32 m0, m0, 0x1000
	v_mfma_f32_16x16x32_bf16 v[50:53], v[192:195], v[162:165], v[50:53]
	v_mfma_f32_16x16x32_bf16 v[46:49], v[192:195], v[166:169], v[46:49]
	v_mfma_f32_16x16x32_bf16 v[42:45], v[192:195], v[170:173], v[42:45]
	global_load_lds_dwordx4 v[142:143], off
	v_lshl_add_u64 v[142:143], v[142:143], 0, s[2:3]
	s_add_i32 m0, m0, 0x1000
	v_mfma_f32_16x16x32_bf16 v[38:41], v[192:195], v[176:179], v[38:41]
	v_mfma_f32_16x16x32_bf16 v[34:37], v[192:195], v[180:183], v[34:37]
	v_mfma_f32_16x16x32_bf16 v[30:33], v[196:199], v[146:149], v[30:33]
	global_load_lds_dwordx4 v[142:143], off
	s_add_i32 m0, m0, 0x1000
	v_lshl_add_u64 v[142:143], v[134:135], 0, s[2:3]
	v_mfma_f32_16x16x32_bf16 v[26:29], v[196:199], v[152:155], v[26:29]
	v_mfma_f32_16x16x32_bf16 v[22:25], v[196:199], v[156:159], v[22:25]
	v_mfma_f32_16x16x32_bf16 v[18:21], v[196:199], v[162:165], v[18:21]
	global_load_lds_dwordx4 v[134:135], off
	s_add_i32 m0, m0, 0x1000
	v_lshl_add_u64 v[132:133], v[132:133], 0, s[14:15]
	v_mfma_f32_16x16x32_bf16 v[14:17], v[196:199], v[166:169], v[14:17]
	v_mfma_f32_16x16x32_bf16 v[10:13], v[196:199], v[170:173], v[10:13]
	v_mfma_f32_16x16x32_bf16 v[6:9], v[196:199], v[176:179], v[6:9]
	global_load_lds_dwordx4 v[142:143], off
	v_lshl_add_u64 v[134:135], v[134:135], 0, s[10:11]
	v_mfma_f32_16x16x32_bf16 v[2:5], v[196:199], v[180:183], v[2:5]
	s_setprio 0
	s_mov_b32 s37, s36
	s_add_i32 s36, s36, 0x6000
	s_cmp_eq_u32 s36, 0x12000
	s_cselect_b32 s36, 0, s36
	s_nop 0
	.p2align 3
	s_waitcnt vmcnt(6) lgkmcnt(0)
	s_barrier
;     ...
;   for (int kt = 0; kt < nk; kt++) {
;     if (kt + 1 < nk) asm volatile("s_waitcnt vmcnt(6)" ::: "memory");
;     else asm volatile("s_waitcnt vmcnt(0)" ::: "memory");
;     __builtin_amdgcn_s_barrier();
;     asm volatile("" ::: "memory");
;     if (kt + 2 < nk) G2_STAGE(kt + 2);
;     const char* cS = smem + (kt % 3) * 24576;
;     bf16x8 xa[8], wb[4];
; #pragma unroll
;     for (int f = 0; f < 8; f++) xa[f] = *(const bf16x8*)(cS + aoff + f * 1024);
; #pragma unroll
;     for (int f = 0; f < 4; f++) wb[f] = *(const bf16x8*)(cS + boff + f * 1024);
; #pragma unroll
;     for (int nf = 0; nf < 4; nf++)
; #pragma unroll
;       for (int mf = 0; mf < 8; mf++)
;         acc[nf][mf] = __builtin_amdgcn_mfma_f32_16x16x32_bf16(wb[nf], xa[mf], acc[nf][mf], 0, 0, 0);
;   }
	s_setprio 1
	v_add_u32_e32 v144, s36, v136
	v_mfma_f32_16x16x32_bf16 v[126:129], v[232:235], v[200:203], v[126:129]
	ds_read_b128 v[146:149], v144 offset:0
	v_mfma_f32_16x16x32_bf16 v[122:125], v[232:235], v[204:207], v[122:125]
	ds_read_b128 v[152:155], v144 offset:1024
	v_mfma_f32_16x16x32_bf16 v[118:121], v[232:235], v[208:211], v[118:121]
	ds_read_b128 v[156:159], v144 offset:2048
	v_mfma_f32_16x16x32_bf16 v[114:117], v[232:235], v[212:215], v[114:117]
	ds_read_b128 v[162:165], v144 offset:3072
	v_mfma_f32_16x16x32_bf16 v[110:113], v[232:235], v[216:219], v[110:113]
	ds_read_b128 v[166:169], v144 offset:4096
	v_mfma_f32_16x16x32_bf16 v[106:109], v[232:235], v[220:223], v[106:109]
	ds_read_b128 v[170:173], v144 offset:5120
	v_mfma_f32_16x16x32_bf16 v[102:105], v[232:235], v[224:227], v[102:105]
	ds_read_b128 v[176:179], v144 offset:6144
	v_mfma_f32_16x16x32_bf16 v[98:101], v[232:235], v[228:231], v[98:101]
	ds_read_b128 v[180:183], v144 offset:7168
	v_mfma_f32_16x16x32_bf16 v[94:97], v[236:239], v[200:203], v[94:97]
	v_add_u32_e64 v144, s36, v137
	v_mfma_f32_16x16x32_bf16 v[90:93], v[236:239], v[204:207], v[90:93]
	v_mfma_f32_16x16x32_bf16 v[86:89], v[236:239], v[208:211], v[86:89]
	ds_read_b128 v[184:187], v144 offset:16384
	v_mfma_f32_16x16x32_bf16 v[82:85], v[236:239], v[212:215], v[82:85]
	ds_read_b128 v[188:191], v144 offset:17408
	v_mfma_f32_16x16x32_bf16 v[78:81], v[236:239], v[216:219], v[78:81]
	ds_read_b128 v[192:195], v144 offset:18432
	v_mfma_f32_16x16x32_bf16 v[74:77], v[236:239], v[220:223], v[74:77]
	ds_read_b128 v[196:199], v144 offset:19456
	v_mfma_f32_16x16x32_bf16 v[70:73], v[236:239], v[224:227], v[70:73]
	v_mfma_f32_16x16x32_bf16 v[66:69], v[236:239], v[228:231], v[66:69]
	v_mfma_f32_16x16x32_bf16 v[62:65], v[240:243], v[200:203], v[62:65]
	v_mfma_f32_16x16x32_bf16 v[58:61], v[240:243], v[204:207], v[58:61]
	v_mfma_f32_16x16x32_bf16 v[54:57], v[240:243], v[208:211], v[54:57]
	v_mfma_f32_16x16x32_bf16 v[50:53], v[240:243], v[212:215], v[50:53]
	v_mfma_f32_16x16x32_bf16 v[46:49], v[240:243], v[216:219], v[46:49]
	v_mfma_f32_16x16x32_bf16 v[42:45], v[240:243], v[220:223], v[42:45]
	v_mfma_f32_16x16x32_bf16 v[38:41], v[240:243], v[224:227], v[38:41]
	v_mfma_f32_16x16x32_bf16 v[34:37], v[240:243], v[228:231], v[34:37]
	v_mfma_f32_16x16x32_bf16 v[30:33], v[244:247], v[200:203], v[30:33]
	v_mfma_f32_16x16x32_bf16 v[26:29], v[244:247], v[204:207], v[26:29]
	v_mfma_f32_16x16x32_bf16 v[22:25], v[244:247], v[208:211], v[22:25]
	v_mfma_f32_16x16x32_bf16 v[18:21], v[244:247], v[212:215], v[18:21]
	v_mfma_f32_16x16x32_bf16 v[14:17], v[244:247], v[216:219], v[14:17]
	v_mfma_f32_16x16x32_bf16 v[10:13], v[244:247], v[220:223], v[10:13]
	v_mfma_f32_16x16x32_bf16 v[6:9], v[244:247], v[224:227], v[6:9]
	v_mfma_f32_16x16x32_bf16 v[2:5], v[244:247], v[228:231], v[2:5]
	s_setprio 0
	s_mov_b32 s37, s36
	s_add_i32 s36, s36, 0x6000
	s_cmp_eq_u32 s36, 0x12000
	s_cselect_b32 s36, 0, s36
	s_nop 0
	.p2align 3
	s_waitcnt vmcnt(0) lgkmcnt(0)
	s_barrier
	s_setprio 1
	v_add_u32_e32 v144, s36, v136
	v_mfma_f32_16x16x32_bf16 v[126:129], v[184:187], v[146:149], v[126:129]
	ds_read_b128 v[200:203], v144 offset:0
	v_mfma_f32_16x16x32_bf16 v[122:125], v[184:187], v[152:155], v[122:125]
	ds_read_b128 v[204:207], v144 offset:1024
	v_mfma_f32_16x16x32_bf16 v[118:121], v[184:187], v[156:159], v[118:121]
	ds_read_b128 v[208:211], v144 offset:2048
	v_mfma_f32_16x16x32_bf16 v[114:117], v[184:187], v[162:165], v[114:117]
	ds_read_b128 v[212:215], v144 offset:3072
	v_mfma_f32_16x16x32_bf16 v[110:113], v[184:187], v[166:169], v[110:113]
	ds_read_b128 v[216:219], v144 offset:4096
	v_mfma_f32_16x16x32_bf16 v[106:109], v[184:187], v[170:173], v[106:109]
	ds_read_b128 v[220:223], v144 offset:5120
	v_mfma_f32_16x16x32_bf16 v[102:105], v[184:187], v[176:179], v[102:105]
	ds_read_b128 v[224:227], v144 offset:6144
	v_mfma_f32_16x16x32_bf16 v[98:101], v[184:187], v[180:183], v[98:101]
	ds_read_b128 v[228:231], v144 offset:7168
	v_mfma_f32_16x16x32_bf16 v[94:97], v[188:191], v[146:149], v[94:97]
	v_add_u32_e64 v144, s36, v137
	v_mfma_f32_16x16x32_bf16 v[90:93], v[188:191], v[152:155], v[90:93]
	v_mfma_f32_16x16x32_bf16 v[86:89], v[188:191], v[156:159], v[86:89]
	ds_read_b128 v[232:235], v144 offset:16384
	v_mfma_f32_16x16x32_bf16 v[82:85], v[188:191], v[162:165], v[82:85]
	ds_read_b128 v[236:239], v144 offset:17408
	v_mfma_f32_16x16x32_bf16 v[78:81], v[188:191], v[166:169], v[78:81]
	ds_read_b128 v[240:243], v144 offset:18432
	v_mfma_f32_16x16x32_bf16 v[74:77], v[188:191], v[170:173], v[74:77]
	ds_read_b128 v[244:247], v144 offset:19456
	v_mfma_f32_16x16x32_bf16 v[70:73], v[188:191], v[176:179], v[70:73]
	v_mfma_f32_16x16x32_bf16 v[66:69], v[188:191], v[180:183], v[66:69]
	v_mfma_f32_16x16x32_bf16 v[62:65], v[192:195], v[146:149], v[62:65]
	v_mfma_f32_16x16x32_bf16 v[58:61], v[192:195], v[152:155], v[58:61]
	v_mfma_f32_16x16x32_bf16 v[54:57], v[192:195], v[156:159], v[54:57]
	v_mfma_f32_16x16x32_bf16 v[50:53], v[192:195], v[162:165], v[50:53]
	v_mfma_f32_16x16x32_bf16 v[46:49], v[192:195], v[166:169], v[46:49]
	v_mfma_f32_16x16x32_bf16 v[42:45], v[192:195], v[170:173], v[42:45]
	v_mfma_f32_16x16x32_bf16 v[38:41], v[192:195], v[176:179], v[38:41]
	v_mfma_f32_16x16x32_bf16 v[34:37], v[192:195], v[180:183], v[34:37]
	v_mfma_f32_16x16x32_bf16 v[30:33], v[196:199], v[146:149], v[30:33]
	v_mfma_f32_16x16x32_bf16 v[26:29], v[196:199], v[152:155], v[26:29]
	v_mfma_f32_16x16x32_bf16 v[22:25], v[196:199], v[156:159], v[22:25]
	v_mfma_f32_16x16x32_bf16 v[18:21], v[196:199], v[162:165], v[18:21]
	v_mfma_f32_16x16x32_bf16 v[14:17], v[196:199], v[166:169], v[14:17]
	v_mfma_f32_16x16x32_bf16 v[10:13], v[196:199], v[170:173], v[10:13]
	v_mfma_f32_16x16x32_bf16 v[6:9], v[196:199], v[176:179], v[6:9]
	v_mfma_f32_16x16x32_bf16 v[2:5], v[196:199], v[180:183], v[2:5]
	s_setprio 0
	s_mov_b32 s37, s36
	s_add_i32 s36, s36, 0x6000
	s_cmp_eq_u32 s36, 0x12000
	s_cselect_b32 s36, 0, s36
	s_nop 0
	.p2align 3
	s_waitcnt lgkmcnt(0)
; DEVI unsigned pack2(float a, float b) { return __builtin_bit_cast(unsigned, __builtin_convertvector((f32x2_t){a, b}, bf16x2_t)); }
; DEVI float siluf_(float x) { return x * __builtin_amdgcn_rcpf(1.f + __expf(-x)); }
;     ...
;     for (int nf = 0; nf < 4; nf++)
; #pragma unroll
;       for (int mf = 0; mf < 8; mf++)
;         acc[nf][mf] = __builtin_amdgcn_mfma_f32_16x16x32_bf16(wb[nf], xa[mf], acc[nf][mf], 0, 0, 0);
;   }
;     ...
; #pragma unroll
;   for (int mf = 0; mf < 8; mf++) {
;     const int row = m0 + wm * 128 + mf * 16 + r16;
;     if (EPI == EPI_SWIGLU) {
; #pragma unroll
;       for (int nf = 0; nf < 2; nf++) {
;         const int hcol = (n0 >> 1) + wn * 32 + nf * 16 + quad * 4;
;         f32x4 g = acc[nf][mf], u = acc[nf + 2][mf];
;         u32x2 pk;
;         pk[0] = pack2(siluf_(g[0]) * u[0], siluf_(g[1]) * u[1]);
;         pk[1] = pack2(siluf_(g[2]) * u[2], siluf_(g[3]) * u[3]);
;         *(u32x2*)(outb + (size_t)row * DFF + hcol) = pk;
;       }
	s_nop 0
	v_mfma_f32_16x16x32_bf16 v[126:129], v[232:235], v[200:203], v[126:129]
	v_mfma_f32_16x16x32_bf16 v[122:125], v[232:235], v[204:207], v[122:125]
	v_mfma_f32_16x16x32_bf16 v[118:121], v[232:235], v[208:211], v[118:121]
	v_mfma_f32_16x16x32_bf16 v[114:117], v[232:235], v[212:215], v[114:117]
	v_mfma_f32_16x16x32_bf16 v[110:113], v[232:235], v[216:219], v[110:113]
	v_mfma_f32_16x16x32_bf16 v[106:109], v[232:235], v[220:223], v[106:109]
	v_mfma_f32_16x16x32_bf16 v[102:105], v[232:235], v[224:227], v[102:105]
	v_mfma_f32_16x16x32_bf16 v[98:101], v[232:235], v[228:231], v[98:101]
	v_mfma_f32_16x16x32_bf16 v[94:97], v[236:239], v[200:203], v[94:97]
	v_mfma_f32_16x16x32_bf16 v[90:93], v[236:239], v[204:207], v[90:93]
	v_mfma_f32_16x16x32_bf16 v[86:89], v[236:239], v[208:211], v[86:89]
	v_mfma_f32_16x16x32_bf16 v[82:85], v[236:239], v[212:215], v[82:85]
	v_mfma_f32_16x16x32_bf16 v[78:81], v[236:239], v[216:219], v[78:81]
	v_mfma_f32_16x16x32_bf16 v[74:77], v[236:239], v[220:223], v[74:77]
	v_mfma_f32_16x16x32_bf16 v[70:73], v[236:239], v[224:227], v[70:73]
	v_mfma_f32_16x16x32_bf16 v[66:69], v[236:239], v[228:231], v[66:69]
	v_mfma_f32_16x16x32_bf16 v[62:65], v[240:243], v[200:203], v[62:65]
	v_mfma_f32_16x16x32_bf16 v[58:61], v[240:243], v[204:207], v[58:61]
	v_mfma_f32_16x16x32_bf16 v[54:57], v[240:243], v[208:211], v[54:57]
	v_mfma_f32_16x16x32_bf16 v[50:53], v[240:243], v[212:215], v[50:53]
	v_mfma_f32_16x16x32_bf16 v[46:49], v[240:243], v[216:219], v[46:49]
	v_mfma_f32_16x16x32_bf16 v[42:45], v[240:243], v[220:223], v[42:45]
	v_mfma_f32_16x16x32_bf16 v[38:41], v[240:243], v[224:227], v[38:41]
	v_mfma_f32_16x16x32_bf16 v[34:37], v[240:243], v[228:231], v[34:37]
	v_mfma_f32_16x16x32_bf16 v[30:33], v[244:247], v[200:203], v[30:33]
	v_mfma_f32_16x16x32_bf16 v[26:29], v[244:247], v[204:207], v[26:29]
	v_mfma_f32_16x16x32_bf16 v[22:25], v[244:247], v[208:211], v[22:25]
	v_mfma_f32_16x16x32_bf16 v[18:21], v[244:247], v[212:215], v[18:21]
	v_mfma_f32_16x16x32_bf16 v[14:17], v[244:247], v[216:219], v[14:17]
	v_mfma_f32_16x16x32_bf16 v[10:13], v[244:247], v[220:223], v[10:13]
	v_mfma_f32_16x16x32_bf16 v[6:9], v[244:247], v[224:227], v[6:9]
	v_mfma_f32_16x16x32_bf16 v[2:5], v[244:247], v[228:231], v[2:5]
	s_mov_b32 m0, s39
	s_mov_b32 s10, 0x16000
	s_mov_b32 s11, 0
	s_mov_b32 s40, 0xbfb8aa3b
	s_nop 7
	v_mov_b32_e32 v224, s40
	v_mov_b32_e32 v225, s40
	v_mov_b32_e32 v226, 1.0
	v_mov_b32_e32 v227, 1.0
	v_pk_mul_f32 v[216:217], v[126:127], v[224:225]
	v_pk_mul_f32 v[218:219], v[128:129], v[224:225]
	v_exp_f32_e32 v216, v216
	v_exp_f32_e32 v217, v217
	v_exp_f32_e32 v218, v218
	v_exp_f32_e32 v219, v219
	v_pk_add_f32 v[216:217], v[216:217], v[226:227]
	v_pk_add_f32 v[218:219], v[218:219], v[226:227]
	v_rcp_f32_e32 v216, v216
	v_rcp_f32_e32 v217, v217
	v_rcp_f32_e32 v218, v218
	v_rcp_f32_e32 v219, v219
	v_pk_mul_f32 v[126:127], v[126:127], v[216:217]
	v_pk_mul_f32 v[128:129], v[128:129], v[218:219]
	v_pk_mul_f32 v[126:127], v[126:127], v[62:63]
	v_pk_mul_f32 v[128:129], v[128:129], v[64:65]
	v_pk_mul_f32 v[220:221], v[94:95], v[224:225]
	v_pk_mul_f32 v[222:223], v[96:97], v[224:225]
	v_exp_f32_e32 v220, v220
	v_exp_f32_e32 v221, v221
	v_exp_f32_e32 v222, v222
	v_exp_f32_e32 v223, v223
	v_pk_add_f32 v[220:221], v[220:221], v[226:227]
	v_pk_add_f32 v[222:223], v[222:223], v[226:227]
	v_rcp_f32_e32 v220, v220
	v_rcp_f32_e32 v221, v221
	v_rcp_f32_e32 v222, v222
	v_rcp_f32_e32 v223, v223
	v_pk_mul_f32 v[94:95], v[94:95], v[220:221]
	v_pk_mul_f32 v[96:97], v[96:97], v[222:223]
	v_pk_mul_f32 v[94:95], v[94:95], v[30:31]
	v_pk_mul_f32 v[96:97], v[96:97], v[32:33]
	v_cvt_pk_bf16_f32 v126, v126, v127
	v_cvt_pk_bf16_f32 v127, v128, v129
	v_cvt_pk_bf16_f32 v128, v94, v95
	v_cvt_pk_bf16_f32 v129, v96, v97
	s_nop 1
	v_permlane16_swap_b32_e32 v126, v128
	v_permlane16_swap_b32_e32 v127, v129
	global_store_dwordx4 v[140:141], v[126:129], off
	v_lshl_add_u64 v[140:141], v[140:141], 0, s[10:11]
	v_pk_mul_f32 v[216:217], v[122:123], v[224:225]
	v_pk_mul_f32 v[218:219], v[124:125], v[224:225]
	v_exp_f32_e32 v216, v216
	v_exp_f32_e32 v217, v217
	v_exp_f32_e32 v218, v218
	v_exp_f32_e32 v219, v219
	v_pk_add_f32 v[216:217], v[216:217], v[226:227]
	v_pk_add_f32 v[218:219], v[218:219], v[226:227]
	v_rcp_f32_e32 v216, v216
	v_rcp_f32_e32 v217, v217
	v_rcp_f32_e32 v218, v218
	v_rcp_f32_e32 v219, v219
	v_pk_mul_f32 v[122:123], v[122:123], v[216:217]
	v_pk_mul_f32 v[124:125], v[124:125], v[218:219]
	v_pk_mul_f32 v[122:123], v[122:123], v[58:59]
	v_pk_mul_f32 v[124:125], v[124:125], v[60:61]
	v_pk_mul_f32 v[220:221], v[90:91], v[224:225]
	v_pk_mul_f32 v[222:223], v[92:93], v[224:225]
	v_exp_f32_e32 v220, v220
	v_exp_f32_e32 v221, v221
	v_exp_f32_e32 v222, v222
	v_exp_f32_e32 v223, v223
	v_pk_add_f32 v[220:221], v[220:221], v[226:227]
	v_pk_add_f32 v[222:223], v[222:223], v[226:227]
	v_rcp_f32_e32 v220, v220
	v_rcp_f32_e32 v221, v221
	v_rcp_f32_e32 v222, v222
	v_rcp_f32_e32 v223, v223
	v_pk_mul_f32 v[90:91], v[90:91], v[220:221]
	v_pk_mul_f32 v[92:93], v[92:93], v[222:223]
	v_pk_mul_f32 v[90:91], v[90:91], v[26:27]
	v_pk_mul_f32 v[92:93], v[92:93], v[28:29]
	v_cvt_pk_bf16_f32 v122, v122, v123
	v_cvt_pk_bf16_f32 v123, v124, v125
	v_cvt_pk_bf16_f32 v124, v90, v91
	v_cvt_pk_bf16_f32 v125, v92, v93
	s_nop 1
	v_permlane16_swap_b32_e32 v122, v124
	v_permlane16_swap_b32_e32 v123, v125
	global_store_dwordx4 v[140:141], v[122:125], off
	v_lshl_add_u64 v[140:141], v[140:141], 0, s[10:11]
	v_pk_mul_f32 v[216:217], v[118:119], v[224:225]
	v_pk_mul_f32 v[218:219], v[120:121], v[224:225]
	v_exp_f32_e32 v216, v216
	v_exp_f32_e32 v217, v217
	v_exp_f32_e32 v218, v218
	v_exp_f32_e32 v219, v219
; DEVI unsigned pack2(float a, float b) { return __builtin_bit_cast(unsigned, __builtin_convertvector((f32x2_t){a, b}, bf16x2_t)); }
; DEVI float siluf_(float x) { return x * __builtin_amdgcn_rcpf(1.f + __expf(-x)); }
;     ...
; #pragma unroll
;   for (int mf = 0; mf < 8; mf++) {
;     const int row = m0 + wm * 128 + mf * 16 + r16;
;     if (EPI == EPI_SWIGLU) {
; #pragma unroll
;       for (int nf = 0; nf < 2; nf++) {
;         const int hcol = (n0 >> 1) + wn * 32 + nf * 16 + quad * 4;
;         f32x4 g = acc[nf][mf], u = acc[nf + 2][mf];
;         u32x2 pk;
;         pk[0] = pack2(siluf_(g[0]) * u[0], siluf_(g[1]) * u[1]);
;         pk[1] = pack2(siluf_(g[2]) * u[2], siluf_(g[3]) * u[3]);
;         *(u32x2*)(outb + (size_t)row * DFF + hcol) = pk;
;       }
	v_pk_add_f32 v[216:217], v[216:217], v[226:227]
	v_pk_add_f32 v[218:219], v[218:219], v[226:227]
	v_rcp_f32_e32 v216, v216
	v_rcp_f32_e32 v217, v217
	v_rcp_f32_e32 v218, v218
	v_rcp_f32_e32 v219, v219
	v_pk_mul_f32 v[118:119], v[118:119], v[216:217]
	v_pk_mul_f32 v[120:121], v[120:121], v[218:219]
	v_pk_mul_f32 v[118:119], v[118:119], v[54:55]
	v_pk_mul_f32 v[120:121], v[120:121], v[56:57]
	v_pk_mul_f32 v[220:221], v[86:87], v[224:225]
	v_pk_mul_f32 v[222:223], v[88:89], v[224:225]
	v_exp_f32_e32 v220, v220
	v_exp_f32_e32 v221, v221
	v_exp_f32_e32 v222, v222
	v_exp_f32_e32 v223, v223
	v_pk_add_f32 v[220:221], v[220:221], v[226:227]
	v_pk_add_f32 v[222:223], v[222:223], v[226:227]
	v_rcp_f32_e32 v220, v220
	v_rcp_f32_e32 v221, v221
	v_rcp_f32_e32 v222, v222
	v_rcp_f32_e32 v223, v223
	v_pk_mul_f32 v[86:87], v[86:87], v[220:221]
	v_pk_mul_f32 v[88:89], v[88:89], v[222:223]
	v_pk_mul_f32 v[86:87], v[86:87], v[22:23]
	v_pk_mul_f32 v[88:89], v[88:89], v[24:25]
	v_cvt_pk_bf16_f32 v118, v118, v119
	v_cvt_pk_bf16_f32 v119, v120, v121
	v_cvt_pk_bf16_f32 v120, v86, v87
	v_cvt_pk_bf16_f32 v121, v88, v89
	s_nop 1
	v_permlane16_swap_b32_e32 v118, v120
	v_permlane16_swap_b32_e32 v119, v121
	global_store_dwordx4 v[140:141], v[118:121], off
	v_lshl_add_u64 v[140:141], v[140:141], 0, s[10:11]
	v_pk_mul_f32 v[216:217], v[114:115], v[224:225]
	v_pk_mul_f32 v[218:219], v[116:117], v[224:225]
	v_exp_f32_e32 v216, v216
	v_exp_f32_e32 v217, v217
	v_exp_f32_e32 v218, v218
	v_exp_f32_e32 v219, v219
	v_pk_add_f32 v[216:217], v[216:217], v[226:227]
	v_pk_add_f32 v[218:219], v[218:219], v[226:227]
	v_rcp_f32_e32 v216, v216
	v_rcp_f32_e32 v217, v217
	v_rcp_f32_e32 v218, v218
	v_rcp_f32_e32 v219, v219
	v_pk_mul_f32 v[114:115], v[114:115], v[216:217]
	v_pk_mul_f32 v[116:117], v[116:117], v[218:219]
	v_pk_mul_f32 v[114:115], v[114:115], v[50:51]
	v_pk_mul_f32 v[116:117], v[116:117], v[52:53]
	v_pk_mul_f32 v[220:221], v[82:83], v[224:225]
	v_pk_mul_f32 v[222:223], v[84:85], v[224:225]
	v_exp_f32_e32 v220, v220
	v_exp_f32_e32 v221, v221
	v_exp_f32_e32 v222, v222
	v_exp_f32_e32 v223, v223
	v_pk_add_f32 v[220:221], v[220:221], v[226:227]
	v_pk_add_f32 v[222:223], v[222:223], v[226:227]
	v_rcp_f32_e32 v220, v220
	v_rcp_f32_e32 v221, v221
	v_rcp_f32_e32 v222, v222
	v_rcp_f32_e32 v223, v223
	v_pk_mul_f32 v[82:83], v[82:83], v[220:221]
	v_pk_mul_f32 v[84:85], v[84:85], v[222:223]
	v_pk_mul_f32 v[82:83], v[82:83], v[18:19]
	v_pk_mul_f32 v[84:85], v[84:85], v[20:21]
	v_cvt_pk_bf16_f32 v114, v114, v115
	v_cvt_pk_bf16_f32 v115, v116, v117
	v_cvt_pk_bf16_f32 v116, v82, v83
	v_cvt_pk_bf16_f32 v117, v84, v85
	s_nop 1
	v_permlane16_swap_b32_e32 v114, v116
	v_permlane16_swap_b32_e32 v115, v117
	global_store_dwordx4 v[140:141], v[114:117], off
	v_lshl_add_u64 v[140:141], v[140:141], 0, s[10:11]
	v_pk_mul_f32 v[216:217], v[110:111], v[224:225]
	v_pk_mul_f32 v[218:219], v[112:113], v[224:225]
	v_exp_f32_e32 v216, v216
	v_exp_f32_e32 v217, v217
	v_exp_f32_e32 v218, v218
	v_exp_f32_e32 v219, v219
	v_pk_add_f32 v[216:217], v[216:217], v[226:227]
	v_pk_add_f32 v[218:219], v[218:219], v[226:227]
	v_rcp_f32_e32 v216, v216
	v_rcp_f32_e32 v217, v217
	v_rcp_f32_e32 v218, v218
	v_rcp_f32_e32 v219, v219
	v_pk_mul_f32 v[110:111], v[110:111], v[216:217]
	v_pk_mul_f32 v[112:113], v[112:113], v[218:219]
	v_pk_mul_f32 v[110:111], v[110:111], v[46:47]
	v_pk_mul_f32 v[112:113], v[112:113], v[48:49]
	v_pk_mul_f32 v[220:221], v[78:79], v[224:225]
	v_pk_mul_f32 v[222:223], v[80:81], v[224:225]
	v_exp_f32_e32 v220, v220
	v_exp_f32_e32 v221, v221
	v_exp_f32_e32 v222, v222
	v_exp_f32_e32 v223, v223
	v_pk_add_f32 v[220:221], v[220:221], v[226:227]
	v_pk_add_f32 v[222:223], v[222:223], v[226:227]
	v_rcp_f32_e32 v220, v220
	v_rcp_f32_e32 v221, v221
	v_rcp_f32_e32 v222, v222
	v_rcp_f32_e32 v223, v223
	v_pk_mul_f32 v[78:79], v[78:79], v[220:221]
	v_pk_mul_f32 v[80:81], v[80:81], v[222:223]
	v_pk_mul_f32 v[78:79], v[78:79], v[14:15]
	v_pk_mul_f32 v[80:81], v[80:81], v[16:17]
	v_cvt_pk_bf16_f32 v110, v110, v111
	v_cvt_pk_bf16_f32 v111, v112, v113
	v_cvt_pk_bf16_f32 v112, v78, v79
	v_cvt_pk_bf16_f32 v113, v80, v81
	s_nop 1
	v_permlane16_swap_b32_e32 v110, v112
	v_permlane16_swap_b32_e32 v111, v113
	global_store_dwordx4 v[140:141], v[110:113], off
	v_lshl_add_u64 v[140:141], v[140:141], 0, s[10:11]
	v_pk_mul_f32 v[216:217], v[106:107], v[224:225]
	v_pk_mul_f32 v[218:219], v[108:109], v[224:225]
	v_exp_f32_e32 v216, v216
; DEVI unsigned pack2(float a, float b) { return __builtin_bit_cast(unsigned, __builtin_convertvector((f32x2_t){a, b}, bf16x2_t)); }
; DEVI float siluf_(float x) { return x * __builtin_amdgcn_rcpf(1.f + __expf(-x)); }
; DEVI int xcd_first_tile() { return (blockIdx.x & 7) * (gridDim.x >> 3) + (blockIdx.x >> 3); }
;     ...
; #pragma unroll
;   for (int mf = 0; mf < 8; mf++) {
;     const int row = m0 + wm * 128 + mf * 16 + r16;
;     if (EPI == EPI_SWIGLU) {
; #pragma unroll
;       for (int nf = 0; nf < 2; nf++) {
;         const int hcol = (n0 >> 1) + wn * 32 + nf * 16 + quad * 4;
;         f32x4 g = acc[nf][mf], u = acc[nf + 2][mf];
;         u32x2 pk;
;         pk[0] = pack2(siluf_(g[0]) * u[0], siluf_(g[1]) * u[1]);
;         pk[1] = pack2(siluf_(g[2]) * u[2], siluf_(g[3]) * u[3]);
;         *(u32x2*)(outb + (size_t)row * DFF + hcol) = pk;
;       }
; DEVI void run_phase(const Params& p, int ph, char* smem) {
;     ...
;       for (int t = xcd_first_tile(); t < 66 * 44; t += xcd_tile_step()) {
;         int mt_, nt_; tile_coords(t, 66, 44, mt_, nt_);
;         gemm_tile256<EPI_SWIGLU>(p, xb, 1024, Bt, 1024, mt_ * 256, nt_ * 128, hb, DFF, smem);
;       }
	v_exp_f32_e32 v217, v217
	v_exp_f32_e32 v218, v218
	v_exp_f32_e32 v219, v219
	v_pk_add_f32 v[216:217], v[216:217], v[226:227]
	v_pk_add_f32 v[218:219], v[218:219], v[226:227]
	v_rcp_f32_e32 v216, v216
	v_rcp_f32_e32 v217, v217
	v_rcp_f32_e32 v218, v218
	v_rcp_f32_e32 v219, v219
	v_pk_mul_f32 v[106:107], v[106:107], v[216:217]
	v_pk_mul_f32 v[108:109], v[108:109], v[218:219]
	v_pk_mul_f32 v[106:107], v[106:107], v[42:43]
	v_pk_mul_f32 v[108:109], v[108:109], v[44:45]
	v_pk_mul_f32 v[220:221], v[74:75], v[224:225]
	v_pk_mul_f32 v[222:223], v[76:77], v[224:225]
	v_exp_f32_e32 v220, v220
	v_exp_f32_e32 v221, v221
	v_exp_f32_e32 v222, v222
	v_exp_f32_e32 v223, v223
	v_pk_add_f32 v[220:221], v[220:221], v[226:227]
	v_pk_add_f32 v[222:223], v[222:223], v[226:227]
	v_rcp_f32_e32 v220, v220
	v_rcp_f32_e32 v221, v221
	v_rcp_f32_e32 v222, v222
	v_rcp_f32_e32 v223, v223
	v_pk_mul_f32 v[74:75], v[74:75], v[220:221]
	v_pk_mul_f32 v[76:77], v[76:77], v[222:223]
	v_pk_mul_f32 v[74:75], v[74:75], v[10:11]
	v_pk_mul_f32 v[76:77], v[76:77], v[12:13]
	v_cvt_pk_bf16_f32 v106, v106, v107
	v_cvt_pk_bf16_f32 v107, v108, v109
	v_cvt_pk_bf16_f32 v108, v74, v75
	v_cvt_pk_bf16_f32 v109, v76, v77
	s_nop 1
	v_permlane16_swap_b32_e32 v106, v108
	v_permlane16_swap_b32_e32 v107, v109
	global_store_dwordx4 v[140:141], v[106:109], off
	v_lshl_add_u64 v[140:141], v[140:141], 0, s[10:11]
	v_pk_mul_f32 v[216:217], v[102:103], v[224:225]
	v_pk_mul_f32 v[218:219], v[104:105], v[224:225]
	v_exp_f32_e32 v216, v216
	v_exp_f32_e32 v217, v217
	v_exp_f32_e32 v218, v218
	v_exp_f32_e32 v219, v219
	v_pk_add_f32 v[216:217], v[216:217], v[226:227]
	v_pk_add_f32 v[218:219], v[218:219], v[226:227]
	v_rcp_f32_e32 v216, v216
	v_rcp_f32_e32 v217, v217
	v_rcp_f32_e32 v218, v218
	v_rcp_f32_e32 v219, v219
	v_pk_mul_f32 v[102:103], v[102:103], v[216:217]
	v_pk_mul_f32 v[104:105], v[104:105], v[218:219]
	v_pk_mul_f32 v[102:103], v[102:103], v[38:39]
	v_pk_mul_f32 v[104:105], v[104:105], v[40:41]
	v_pk_mul_f32 v[220:221], v[70:71], v[224:225]
	v_pk_mul_f32 v[222:223], v[72:73], v[224:225]
	v_exp_f32_e32 v220, v220
	v_exp_f32_e32 v221, v221
	v_exp_f32_e32 v222, v222
	v_exp_f32_e32 v223, v223
	v_pk_add_f32 v[220:221], v[220:221], v[226:227]
	v_pk_add_f32 v[222:223], v[222:223], v[226:227]
	v_rcp_f32_e32 v220, v220
	v_rcp_f32_e32 v221, v221
	v_rcp_f32_e32 v222, v222
	v_rcp_f32_e32 v223, v223
	v_pk_mul_f32 v[70:71], v[70:71], v[220:221]
	v_pk_mul_f32 v[72:73], v[72:73], v[222:223]
	v_pk_mul_f32 v[70:71], v[70:71], v[6:7]
	v_pk_mul_f32 v[72:73], v[72:73], v[8:9]
	v_cvt_pk_bf16_f32 v102, v102, v103
	v_cvt_pk_bf16_f32 v103, v104, v105
	v_cvt_pk_bf16_f32 v104, v70, v71
	v_cvt_pk_bf16_f32 v105, v72, v73
	s_nop 1
	v_permlane16_swap_b32_e32 v102, v104
	v_permlane16_swap_b32_e32 v103, v105
	global_store_dwordx4 v[140:141], v[102:105], off
	v_lshl_add_u64 v[140:141], v[140:141], 0, s[10:11]
	v_pk_mul_f32 v[216:217], v[98:99], v[224:225]
	v_pk_mul_f32 v[218:219], v[100:101], v[224:225]
	v_exp_f32_e32 v216, v216
	v_exp_f32_e32 v217, v217
	v_exp_f32_e32 v218, v218
	v_exp_f32_e32 v219, v219
	v_pk_add_f32 v[216:217], v[216:217], v[226:227]
	v_pk_add_f32 v[218:219], v[218:219], v[226:227]
	v_rcp_f32_e32 v216, v216
	v_rcp_f32_e32 v217, v217
	v_rcp_f32_e32 v218, v218
	v_rcp_f32_e32 v219, v219
	v_pk_mul_f32 v[98:99], v[98:99], v[216:217]
	v_pk_mul_f32 v[100:101], v[100:101], v[218:219]
	v_pk_mul_f32 v[98:99], v[98:99], v[34:35]
	v_pk_mul_f32 v[100:101], v[100:101], v[36:37]
	v_pk_mul_f32 v[220:221], v[66:67], v[224:225]
	v_pk_mul_f32 v[222:223], v[68:69], v[224:225]
	v_exp_f32_e32 v220, v220
	v_exp_f32_e32 v221, v221
	v_exp_f32_e32 v222, v222
	v_exp_f32_e32 v223, v223
	v_pk_add_f32 v[220:221], v[220:221], v[226:227]
	v_pk_add_f32 v[222:223], v[222:223], v[226:227]
	v_rcp_f32_e32 v220, v220
	v_rcp_f32_e32 v221, v221
	v_rcp_f32_e32 v222, v222
	v_rcp_f32_e32 v223, v223
	v_pk_mul_f32 v[66:67], v[66:67], v[220:221]
	v_pk_mul_f32 v[68:69], v[68:69], v[222:223]
	v_pk_mul_f32 v[66:67], v[66:67], v[2:3]
	v_pk_mul_f32 v[68:69], v[68:69], v[4:5]
	v_cvt_pk_bf16_f32 v98, v98, v99
	v_cvt_pk_bf16_f32 v99, v100, v101
	v_cvt_pk_bf16_f32 v100, v66, v67
	v_cvt_pk_bf16_f32 v101, v68, v69
	s_nop 1
	v_permlane16_swap_b32_e32 v98, v100
	v_permlane16_swap_b32_e32 v99, v101
	global_store_dwordx4 v[140:141], v[98:101], off
	v_readlane_b32 s42, v250, 7
	s_add_i32 s8, s8, s42
	s_cmpk_gt_i32 s8, 0xb57
	s_cbranch_scc0 .LBB0_124
	s_branch .LBB0_131

;     ...
;   __syncthreads();
;   G2_STAGE(0); G2_STAGE(1);
;   const int fsw = (0x78 >> (((r16 >> 2) & 3) * 2)) & 3;
;   const int aoff = (wm * 128 + r16) * 64 + ((quad ^ fsw) << 4);
;   const int boff = 16384 + (wn * 64 + r16) * 64 + ((quad ^ fsw) << 4);
;   for (int kt = 0; kt < nk; kt++) {
;     if (kt + 1 < nk) asm volatile("s_waitcnt vmcnt(6)" ::: "memory");
;     else asm volatile("s_waitcnt vmcnt(0)" ::: "memory");
;     __builtin_amdgcn_s_barrier();
;     asm volatile("" ::: "memory");
;     if (kt + 2 < nk) G2_STAGE(kt + 2);
;     const char* cS = smem + (kt % 3) * 24576;
;     bf16x8 xa[8], wb[4];
; #pragma unroll
;     for (int f = 0; f < 8; f++) xa[f] = *(const bf16x8*)(cS + aoff + f * 1024);
; #pragma unroll
;     for (int f = 0; f < 4; f++) wb[f] = *(const bf16x8*)(cS + boff + f * 1024);
; #pragma unroll
;     for (int nf = 0; nf < 4; nf++)
; #pragma unroll
;       for (int mf = 0; mf < 8; mf++)
;         acc[nf][mf] = __builtin_amdgcn_mfma_f32_16x16x32_bf16(wb[nf], xa[mf], acc[nf][mf], 0, 0, 0);
;   }
.Lt0_loop:
	.p2align 3
	s_waitcnt vmcnt(6) lgkmcnt(0)
	s_barrier
	s_setprio 1
	v_add_u32_e32 v144, s38, v136
	v_mfma_f32_16x16x32_bf16 v[126:129], v[184:187], v[146:149], v[126:129]
	ds_read_b128 v[200:203], v144 offset:0
	v_mfma_f32_16x16x32_bf16 v[122:125], v[184:187], v[152:155], v[122:125]
	ds_read_b128 v[204:207], v144 offset:1024
	v_mfma_f32_16x16x32_bf16 v[118:121], v[184:187], v[156:159], v[118:121]
	ds_read_b128 v[208:211], v144 offset:2048
	v_mfma_f32_16x16x32_bf16 v[114:117], v[184:187], v[162:165], v[114:117]
	ds_read_b128 v[212:215], v144 offset:3072
	v_mfma_f32_16x16x32_bf16 v[110:113], v[184:187], v[166:169], v[110:113]
	ds_read_b128 v[216:219], v144 offset:4096
	v_mfma_f32_16x16x32_bf16 v[106:109], v[184:187], v[170:173], v[106:109]
	ds_read_b128 v[220:223], v144 offset:5120
	v_mfma_f32_16x16x32_bf16 v[102:105], v[184:187], v[176:179], v[102:105]
	ds_read_b128 v[224:227], v144 offset:6144
	v_mfma_f32_16x16x32_bf16 v[98:101], v[184:187], v[180:183], v[98:101]
	ds_read_b128 v[228:231], v144 offset:7168
	v_mfma_f32_16x16x32_bf16 v[94:97], v[188:191], v[146:149], v[94:97]
	v_add_u32_e64 v144, s38, v137
	v_mfma_f32_16x16x32_bf16 v[90:93], v[188:191], v[152:155], v[90:93]
	v_mfma_f32_16x16x32_bf16 v[86:89], v[188:191], v[156:159], v[86:89]
	ds_read_b128 v[232:235], v144 offset:16384
	v_mfma_f32_16x16x32_bf16 v[82:85], v[188:191], v[162:165], v[82:85]
	ds_read_b128 v[236:239], v144 offset:17408
	v_mfma_f32_16x16x32_bf16 v[78:81], v[188:191], v[166:169], v[78:81]
	ds_read_b128 v[240:243], v144 offset:18432
	v_mfma_f32_16x16x32_bf16 v[74:77], v[188:191], v[170:173], v[74:77]
	ds_read_b128 v[244:247], v144 offset:19456
	v_mfma_f32_16x16x32_bf16 v[70:73], v[188:191], v[176:179], v[70:73]
	s_add_i32 s40, s44, s39
	s_mov_b32 m0, s40
	v_lshl_add_u64 v[142:143], v[132:133], 0, s[2:3]
	v_mfma_f32_16x16x32_bf16 v[66:69], v[188:191], v[180:183], v[66:69]
	global_load_lds_dwordx4 v[132:133], off
	s_add_i32 m0, m0, 0x1000
	v_mfma_f32_16x16x32_bf16 v[62:65], v[192:195], v[146:149], v[62:65]
	v_mfma_f32_16x16x32_bf16 v[58:61], v[192:195], v[152:155], v[58:61]
	v_mfma_f32_16x16x32_bf16 v[54:57], v[192:195], v[156:159], v[54:57]
	global_load_lds_dwordx4 v[142:143], off
	v_lshl_add_u64 v[142:143], v[142:143], 0, s[2:3]
	s_add_i32 m0, m0, 0x1000
	v_mfma_f32_16x16x32_bf16 v[50:53], v[192:195], v[162:165], v[50:53]
	v_mfma_f32_16x16x32_bf16 v[46:49], v[192:195], v[166:169], v[46:49]
	v_mfma_f32_16x16x32_bf16 v[42:45], v[192:195], v[170:173], v[42:45]
	global_load_lds_dwordx4 v[142:143], off
	v_lshl_add_u64 v[142:143], v[142:143], 0, s[2:3]
	s_add_i32 m0, m0, 0x1000
	v_mfma_f32_16x16x32_bf16 v[38:41], v[192:195], v[176:179], v[38:41]
	v_mfma_f32_16x16x32_bf16 v[34:37], v[192:195], v[180:183], v[34:37]
	v_mfma_f32_16x16x32_bf16 v[30:33], v[196:199], v[146:149], v[30:33]
	global_load_lds_dwordx4 v[142:143], off
	s_add_i32 m0, m0, 0x1000
	v_lshl_add_u64 v[142:143], v[134:135], 0, s[2:3]
	v_mfma_f32_16x16x32_bf16 v[26:29], v[196:199], v[152:155], v[26:29]
	v_mfma_f32_16x16x32_bf16 v[22:25], v[196:199], v[156:159], v[22:25]
	v_mfma_f32_16x16x32_bf16 v[18:21], v[196:199], v[162:165], v[18:21]
	global_load_lds_dwordx4 v[134:135], off
	s_add_i32 m0, m0, 0x1000
	v_lshl_add_u64 v[132:133], v[132:133], 0, s[36:37]
	v_mfma_f32_16x16x32_bf16 v[14:17], v[196:199], v[166:169], v[14:17]
	v_mfma_f32_16x16x32_bf16 v[10:13], v[196:199], v[170:173], v[10:13]
	v_mfma_f32_16x16x32_bf16 v[6:9], v[196:199], v[176:179], v[6:9]
	global_load_lds_dwordx4 v[142:143], off
	v_lshl_add_u64 v[134:135], v[134:135], 0, s[8:9]
	v_mfma_f32_16x16x32_bf16 v[2:5], v[196:199], v[180:183], v[2:5]
	s_setprio 0
	s_mov_b32 s39, s38
	s_add_i32 s38, s38, 0x6000
	s_cmp_eq_u32 s38, 0x12000
	s_cselect_b32 s38, 0, s38
	s_nop 0
	.p2align 3
	s_waitcnt vmcnt(6) lgkmcnt(0)
	s_barrier
	s_setprio 1
	v_add_u32_e32 v144, s38, v136
	v_mfma_f32_16x16x32_bf16 v[126:129], v[232:235], v[200:203], v[126:129]
	ds_read_b128 v[146:149], v144 offset:0
	v_mfma_f32_16x16x32_bf16 v[122:125], v[232:235], v[204:207], v[122:125]
	ds_read_b128 v[152:155], v144 offset:1024
	v_mfma_f32_16x16x32_bf16 v[118:121], v[232:235], v[208:211], v[118:121]
	ds_read_b128 v[156:159], v144 offset:2048
	v_mfma_f32_16x16x32_bf16 v[114:117], v[232:235], v[212:215], v[114:117]
	ds_read_b128 v[162:165], v144 offset:3072
	v_mfma_f32_16x16x32_bf16 v[110:113], v[232:235], v[216:219], v[110:113]
	ds_read_b128 v[166:169], v144 offset:4096
	v_mfma_f32_16x16x32_bf16 v[106:109], v[232:235], v[220:223], v[106:109]
	ds_read_b128 v[170:173], v144 offset:5120
	v_mfma_f32_16x16x32_bf16 v[102:105], v[232:235], v[224:227], v[102:105]
	ds_read_b128 v[176:179], v144 offset:6144
	v_mfma_f32_16x16x32_bf16 v[98:101], v[232:235], v[228:231], v[98:101]
	ds_read_b128 v[180:183], v144 offset:7168
	v_mfma_f32_16x16x32_bf16 v[94:97], v[236:239], v[200:203], v[94:97]
	v_add_u32_e64 v144, s38, v137
	v_mfma_f32_16x16x32_bf16 v[90:93], v[236:239], v[204:207], v[90:93]
	v_mfma_f32_16x16x32_bf16 v[86:89], v[236:239], v[208:211], v[86:89]
	ds_read_b128 v[184:187], v144 offset:16384
	v_mfma_f32_16x16x32_bf16 v[82:85], v[236:239], v[212:215], v[82:85]
	ds_read_b128 v[188:191], v144 offset:17408
	v_mfma_f32_16x16x32_bf16 v[78:81], v[236:239], v[216:219], v[78:81]
	ds_read_b128 v[192:195], v144 offset:18432
	v_mfma_f32_16x16x32_bf16 v[74:77], v[236:239], v[220:223], v[74:77]
	ds_read_b128 v[196:199], v144 offset:19456
	v_mfma_f32_16x16x32_bf16 v[70:73], v[236:239], v[224:227], v[70:73]
	s_add_i32 s40, s44, s39
	s_mov_b32 m0, s40
	v_lshl_add_u64 v[142:143], v[132:133], 0, s[2:3]
	v_mfma_f32_16x16x32_bf16 v[66:69], v[236:239], v[228:231], v[66:69]
	global_load_lds_dwordx4 v[132:133], off
;     ...
;   __syncthreads();
;   G2_STAGE(0); G2_STAGE(1);
;   const int fsw = (0x78 >> (((r16 >> 2) & 3) * 2)) & 3;
;   const int aoff = (wm * 128 + r16) * 64 + ((quad ^ fsw) << 4);
;   const int boff = 16384 + (wn * 64 + r16) * 64 + ((quad ^ fsw) << 4);
;   for (int kt = 0; kt < nk; kt++) {
;     if (kt + 1 < nk) asm volatile("s_waitcnt vmcnt(6)" ::: "memory");
;     else asm volatile("s_waitcnt vmcnt(0)" ::: "memory");
;     __builtin_amdgcn_s_barrier();
;     asm volatile("" ::: "memory");
;     if (kt + 2 < nk) G2_STAGE(kt + 2);
;     const char* cS = smem + (kt % 3) * 24576;
;     bf16x8 xa[8], wb[4];
; #pragma unroll
;     for (int f = 0; f < 8; f++) xa[f] = *(const bf16x8*)(cS + aoff + f * 1024);
; #pragma unroll
;     for (int f = 0; f < 4; f++) wb[f] = *(const bf16x8*)(cS + boff + f * 1024);
; #pragma unroll
;     for (int nf = 0; nf < 4; nf++)
; #pragma unroll
;       for (int mf = 0; mf < 8; mf++)
;         acc[nf][mf] = __builtin_amdgcn_mfma_f32_16x16x32_bf16(wb[nf], xa[mf], acc[nf][mf], 0, 0, 0);
;   }
	s_add_i32 m0, m0, 0x1000
	v_mfma_f32_16x16x32_bf16 v[62:65], v[240:243], v[200:203], v[62:65]
	v_mfma_f32_16x16x32_bf16 v[58:61], v[240:243], v[204:207], v[58:61]
	v_mfma_f32_16x16x32_bf16 v[54:57], v[240:243], v[208:211], v[54:57]
	global_load_lds_dwordx4 v[142:143], off
	v_lshl_add_u64 v[142:143], v[142:143], 0, s[2:3]
	s_add_i32 m0, m0, 0x1000
	v_mfma_f32_16x16x32_bf16 v[50:53], v[240:243], v[212:215], v[50:53]
	v_mfma_f32_16x16x32_bf16 v[46:49], v[240:243], v[216:219], v[46:49]
	v_mfma_f32_16x16x32_bf16 v[42:45], v[240:243], v[220:223], v[42:45]
	global_load_lds_dwordx4 v[142:143], off
	v_lshl_add_u64 v[142:143], v[142:143], 0, s[2:3]
	s_add_i32 m0, m0, 0x1000
	v_mfma_f32_16x16x32_bf16 v[38:41], v[240:243], v[224:227], v[38:41]
	v_mfma_f32_16x16x32_bf16 v[34:37], v[240:243], v[228:231], v[34:37]
	v_mfma_f32_16x16x32_bf16 v[30:33], v[244:247], v[200:203], v[30:33]
	global_load_lds_dwordx4 v[142:143], off
	s_add_i32 m0, m0, 0x1000
	v_lshl_add_u64 v[142:143], v[134:135], 0, s[2:3]
	v_mfma_f32_16x16x32_bf16 v[26:29], v[244:247], v[204:207], v[26:29]
	v_mfma_f32_16x16x32_bf16 v[22:25], v[244:247], v[208:211], v[22:25]
	v_mfma_f32_16x16x32_bf16 v[18:21], v[244:247], v[212:215], v[18:21]
	global_load_lds_dwordx4 v[134:135], off
	s_add_i32 m0, m0, 0x1000
	v_lshl_add_u64 v[132:133], v[132:133], 0, s[36:37]
	v_mfma_f32_16x16x32_bf16 v[14:17], v[244:247], v[216:219], v[14:17]
	v_mfma_f32_16x16x32_bf16 v[10:13], v[244:247], v[220:223], v[10:13]
	v_mfma_f32_16x16x32_bf16 v[6:9], v[244:247], v[224:227], v[6:9]
	global_load_lds_dwordx4 v[142:143], off
	v_lshl_add_u64 v[134:135], v[134:135], 0, s[8:9]
	v_mfma_f32_16x16x32_bf16 v[2:5], v[244:247], v[228:231], v[2:5]
	s_setprio 0
	s_mov_b32 s39, s38
	s_add_i32 s38, s38, 0x6000
	s_cmp_eq_u32 s38, 0x12000
	s_cselect_b32 s38, 0, s38
	s_nop 0
	s_sub_i32 s15, s15, 1
	s_cmp_lg_u32 s15, 0
	s_cbranch_scc1 .Lt0_loop
	.p2align 3
	s_waitcnt vmcnt(6) lgkmcnt(0)
	s_barrier
	s_setprio 1
	v_add_u32_e32 v144, s38, v136
	v_mfma_f32_16x16x32_bf16 v[126:129], v[184:187], v[146:149], v[126:129]
	ds_read_b128 v[200:203], v144 offset:0
	v_mfma_f32_16x16x32_bf16 v[122:125], v[184:187], v[152:155], v[122:125]
	ds_read_b128 v[204:207], v144 offset:1024
	v_mfma_f32_16x16x32_bf16 v[118:121], v[184:187], v[156:159], v[118:121]
	ds_read_b128 v[208:211], v144 offset:2048
	v_mfma_f32_16x16x32_bf16 v[114:117], v[184:187], v[162:165], v[114:117]
	ds_read_b128 v[212:215], v144 offset:3072
	v_mfma_f32_16x16x32_bf16 v[110:113], v[184:187], v[166:169], v[110:113]
	ds_read_b128 v[216:219], v144 offset:4096
	v_mfma_f32_16x16x32_bf16 v[106:109], v[184:187], v[170:173], v[106:109]
	ds_read_b128 v[220:223], v144 offset:5120
	v_mfma_f32_16x16x32_bf16 v[102:105], v[184:187], v[176:179], v[102:105]
	ds_read_b128 v[224:227], v144 offset:6144
	v_mfma_f32_16x16x32_bf16 v[98:101], v[184:187], v[180:183], v[98:101]
	ds_read_b128 v[228:231], v144 offset:7168
	v_mfma_f32_16x16x32_bf16 v[94:97], v[188:191], v[146:149], v[94:97]
	v_add_u32_e64 v144, s38, v137
	v_mfma_f32_16x16x32_bf16 v[90:93], v[188:191], v[152:155], v[90:93]
	v_mfma_f32_16x16x32_bf16 v[86:89], v[188:191], v[156:159], v[86:89]
	ds_read_b128 v[232:235], v144 offset:16384
	v_mfma_f32_16x16x32_bf16 v[82:85], v[188:191], v[162:165], v[82:85]
	ds_read_b128 v[236:239], v144 offset:17408
	v_mfma_f32_16x16x32_bf16 v[78:81], v[188:191], v[166:169], v[78:81]
	ds_read_b128 v[240:243], v144 offset:18432
	v_mfma_f32_16x16x32_bf16 v[74:77], v[188:191], v[170:173], v[74:77]
	ds_read_b128 v[244:247], v144 offset:19456
	v_mfma_f32_16x16x32_bf16 v[70:73], v[188:191], v[176:179], v[70:73]
	s_add_i32 s40, s44, s39
	s_mov_b32 m0, s40
	v_lshl_add_u64 v[142:143], v[132:133], 0, s[2:3]
	v_mfma_f32_16x16x32_bf16 v[66:69], v[188:191], v[180:183], v[66:69]
	global_load_lds_dwordx4 v[132:133], off
	s_add_i32 m0, m0, 0x1000
	v_mfma_f32_16x16x32_bf16 v[62:65], v[192:195], v[146:149], v[62:65]
	v_mfma_f32_16x16x32_bf16 v[58:61], v[192:195], v[152:155], v[58:61]
	v_mfma_f32_16x16x32_bf16 v[54:57], v[192:195], v[156:159], v[54:57]
	global_load_lds_dwordx4 v[142:143], off
	v_lshl_add_u64 v[142:143], v[142:143], 0, s[2:3]
	s_add_i32 m0, m0, 0x1000
	v_mfma_f32_16x16x32_bf16 v[50:53], v[192:195], v[162:165], v[50:53]
	v_mfma_f32_16x16x32_bf16 v[46:49], v[192:195], v[166:169], v[46:49]
	v_mfma_f32_16x16x32_bf16 v[42:45], v[192:195], v[170:173], v[42:45]
	global_load_lds_dwordx4 v[142:143], off
	v_lshl_add_u64 v[142:143], v[142:143], 0, s[2:3]
	s_add_i32 m0, m0, 0x1000
	v_mfma_f32_16x16x32_bf16 v[38:41], v[192:195], v[176:179], v[38:41]
	v_mfma_f32_16x16x32_bf16 v[34:37], v[192:195], v[180:183], v[34:37]
	v_mfma_f32_16x16x32_bf16 v[30:33], v[196:199], v[146:149], v[30:33]
	global_load_lds_dwordx4 v[142:143], off
	s_add_i32 m0, m0, 0x1000
	v_lshl_add_u64 v[142:143], v[134:135], 0, s[2:3]
	v_mfma_f32_16x16x32_bf16 v[26:29], v[196:199], v[152:155], v[26:29]
	v_mfma_f32_16x16x32_bf16 v[22:25], v[196:199], v[156:159], v[22:25]
	v_mfma_f32_16x16x32_bf16 v[18:21], v[196:199], v[162:165], v[18:21]
	global_load_lds_dwordx4 v[134:135], off
	s_add_i32 m0, m0, 0x1000
	v_lshl_add_u64 v[132:133], v[132:133], 0, s[36:37]
	v_mfma_f32_16x16x32_bf16 v[14:17], v[196:199], v[166:169], v[14:17]
	v_mfma_f32_16x16x32_bf16 v[10:13], v[196:199], v[170:173], v[10:13]
	v_mfma_f32_16x16x32_bf16 v[6:9], v[196:199], v[176:179], v[6:9]
	global_load_lds_dwordx4 v[142:143], off
	v_lshl_add_u64 v[134:135], v[134:135], 0, s[8:9]
	v_mfma_f32_16x16x32_bf16 v[2:5], v[196:199], v[180:183], v[2:5]
	s_setprio 0
	s_mov_b32 s39, s38
	s_add_i32 s38, s38, 0x6000
	s_cmp_eq_u32 s38, 0x12000
	s_cselect_b32 s38, 0, s38
	s_nop 0
	.p2align 3
	s_waitcnt vmcnt(6) lgkmcnt(0)
	s_barrier
;     ...
;   for (int kt = 0; kt < nk; kt++) {
;     if (kt + 1 < nk) asm volatile("s_waitcnt vmcnt(6)" ::: "memory");
;     else asm volatile("s_waitcnt vmcnt(0)" ::: "memory");
;     __builtin_amdgcn_s_barrier();
;     asm volatile("" ::: "memory");
;     if (kt + 2 < nk) G2_STAGE(kt + 2);
;     const char* cS = smem + (kt % 3) * 24576;
;     bf16x8 xa[8], wb[4];
; #pragma unroll
;     for (int f = 0; f < 8; f++) xa[f] = *(const bf16x8*)(cS + aoff + f * 1024);
; #pragma unroll
;     for (int f = 0; f < 4; f++) wb[f] = *(const bf16x8*)(cS + boff + f * 1024);
; #pragma unroll
;     for (int nf = 0; nf < 4; nf++)
; #pragma unroll
;       for (int mf = 0; mf < 8; mf++)
;         acc[nf][mf] = __builtin_amdgcn_mfma_f32_16x16x32_bf16(wb[nf], xa[mf], acc[nf][mf], 0, 0, 0);
;   }
	s_setprio 1
	v_add_u32_e32 v144, s38, v136
	v_mfma_f32_16x16x32_bf16 v[126:129], v[232:235], v[200:203], v[126:129]
	ds_read_b128 v[146:149], v144 offset:0
	v_mfma_f32_16x16x32_bf16 v[122:125], v[232:235], v[204:207], v[122:125]
	ds_read_b128 v[152:155], v144 offset:1024
	v_mfma_f32_16x16x32_bf16 v[118:121], v[232:235], v[208:211], v[118:121]
	ds_read_b128 v[156:159], v144 offset:2048
	v_mfma_f32_16x16x32_bf16 v[114:117], v[232:235], v[212:215], v[114:117]
	ds_read_b128 v[162:165], v144 offset:3072
	v_mfma_f32_16x16x32_bf16 v[110:113], v[232:235], v[216:219], v[110:113]
	ds_read_b128 v[166:169], v144 offset:4096
	v_mfma_f32_16x16x32_bf16 v[106:109], v[232:235], v[220:223], v[106:109]
	ds_read_b128 v[170:173], v144 offset:5120
	v_mfma_f32_16x16x32_bf16 v[102:105], v[232:235], v[224:227], v[102:105]
	ds_read_b128 v[176:179], v144 offset:6144
	v_mfma_f32_16x16x32_bf16 v[98:101], v[232:235], v[228:231], v[98:101]
	ds_read_b128 v[180:183], v144 offset:7168
	v_mfma_f32_16x16x32_bf16 v[94:97], v[236:239], v[200:203], v[94:97]
	v_add_u32_e64 v144, s38, v137
	v_mfma_f32_16x16x32_bf16 v[90:93], v[236:239], v[204:207], v[90:93]
	v_mfma_f32_16x16x32_bf16 v[86:89], v[236:239], v[208:211], v[86:89]
	ds_read_b128 v[184:187], v144 offset:16384
	v_mfma_f32_16x16x32_bf16 v[82:85], v[236:239], v[212:215], v[82:85]
	ds_read_b128 v[188:191], v144 offset:17408
	v_mfma_f32_16x16x32_bf16 v[78:81], v[236:239], v[216:219], v[78:81]
	ds_read_b128 v[192:195], v144 offset:18432
	v_mfma_f32_16x16x32_bf16 v[74:77], v[236:239], v[220:223], v[74:77]
	ds_read_b128 v[196:199], v144 offset:19456
	v_mfma_f32_16x16x32_bf16 v[70:73], v[236:239], v[224:227], v[70:73]
	v_mfma_f32_16x16x32_bf16 v[66:69], v[236:239], v[228:231], v[66:69]
	v_mfma_f32_16x16x32_bf16 v[62:65], v[240:243], v[200:203], v[62:65]
	v_mfma_f32_16x16x32_bf16 v[58:61], v[240:243], v[204:207], v[58:61]
	v_mfma_f32_16x16x32_bf16 v[54:57], v[240:243], v[208:211], v[54:57]
	v_mfma_f32_16x16x32_bf16 v[50:53], v[240:243], v[212:215], v[50:53]
	v_mfma_f32_16x16x32_bf16 v[46:49], v[240:243], v[216:219], v[46:49]
	v_mfma_f32_16x16x32_bf16 v[42:45], v[240:243], v[220:223], v[42:45]
	v_mfma_f32_16x16x32_bf16 v[38:41], v[240:243], v[224:227], v[38:41]
	v_mfma_f32_16x16x32_bf16 v[34:37], v[240:243], v[228:231], v[34:37]
	v_mfma_f32_16x16x32_bf16 v[30:33], v[244:247], v[200:203], v[30:33]
	v_mfma_f32_16x16x32_bf16 v[26:29], v[244:247], v[204:207], v[26:29]
	v_mfma_f32_16x16x32_bf16 v[22:25], v[244:247], v[208:211], v[22:25]
	v_mfma_f32_16x16x32_bf16 v[18:21], v[244:247], v[212:215], v[18:21]
	v_mfma_f32_16x16x32_bf16 v[14:17], v[244:247], v[216:219], v[14:17]
	v_mfma_f32_16x16x32_bf16 v[10:13], v[244:247], v[220:223], v[10:13]
	v_mfma_f32_16x16x32_bf16 v[6:9], v[244:247], v[224:227], v[6:9]
	v_mfma_f32_16x16x32_bf16 v[2:5], v[244:247], v[228:231], v[2:5]
	s_setprio 0
	s_mov_b32 s39, s38
	s_add_i32 s38, s38, 0x6000
	s_cmp_eq_u32 s38, 0x12000
	s_cselect_b32 s38, 0, s38
	s_nop 0
	.p2align 3
	s_waitcnt vmcnt(0) lgkmcnt(0)
	s_barrier
	s_setprio 1
	v_add_u32_e32 v144, s38, v136
	v_mfma_f32_16x16x32_bf16 v[126:129], v[184:187], v[146:149], v[126:129]
	ds_read_b128 v[200:203], v144 offset:0
	v_mfma_f32_16x16x32_bf16 v[122:125], v[184:187], v[152:155], v[122:125]
	ds_read_b128 v[204:207], v144 offset:1024
	v_mfma_f32_16x16x32_bf16 v[118:121], v[184:187], v[156:159], v[118:121]
	ds_read_b128 v[208:211], v144 offset:2048
	v_mfma_f32_16x16x32_bf16 v[114:117], v[184:187], v[162:165], v[114:117]
	ds_read_b128 v[212:215], v144 offset:3072
	v_mfma_f32_16x16x32_bf16 v[110:113], v[184:187], v[166:169], v[110:113]
	ds_read_b128 v[216:219], v144 offset:4096
	v_mfma_f32_16x16x32_bf16 v[106:109], v[184:187], v[170:173], v[106:109]
	ds_read_b128 v[220:223], v144 offset:5120
	v_mfma_f32_16x16x32_bf16 v[102:105], v[184:187], v[176:179], v[102:105]
	ds_read_b128 v[224:227], v144 offset:6144
	v_mfma_f32_16x16x32_bf16 v[98:101], v[184:187], v[180:183], v[98:101]
	ds_read_b128 v[228:231], v144 offset:7168
	v_mfma_f32_16x16x32_bf16 v[94:97], v[188:191], v[146:149], v[94:97]
	v_add_u32_e64 v144, s38, v137
	v_mfma_f32_16x16x32_bf16 v[90:93], v[188:191], v[152:155], v[90:93]
	v_mfma_f32_16x16x32_bf16 v[86:89], v[188:191], v[156:159], v[86:89]
	ds_read_b128 v[232:235], v144 offset:16384
	v_mfma_f32_16x16x32_bf16 v[82:85], v[188:191], v[162:165], v[82:85]
	ds_read_b128 v[236:239], v144 offset:17408
	v_mfma_f32_16x16x32_bf16 v[78:81], v[188:191], v[166:169], v[78:81]
	ds_read_b128 v[240:243], v144 offset:18432
	v_mfma_f32_16x16x32_bf16 v[74:77], v[188:191], v[170:173], v[74:77]
	ds_read_b128 v[244:247], v144 offset:19456
	v_mfma_f32_16x16x32_bf16 v[70:73], v[188:191], v[176:179], v[70:73]
	v_mfma_f32_16x16x32_bf16 v[66:69], v[188:191], v[180:183], v[66:69]
	v_mfma_f32_16x16x32_bf16 v[62:65], v[192:195], v[146:149], v[62:65]
	v_mfma_f32_16x16x32_bf16 v[58:61], v[192:195], v[152:155], v[58:61]
	v_mfma_f32_16x16x32_bf16 v[54:57], v[192:195], v[156:159], v[54:57]
	v_mfma_f32_16x16x32_bf16 v[50:53], v[192:195], v[162:165], v[50:53]
	v_mfma_f32_16x16x32_bf16 v[46:49], v[192:195], v[166:169], v[46:49]
	v_mfma_f32_16x16x32_bf16 v[42:45], v[192:195], v[170:173], v[42:45]
	v_mfma_f32_16x16x32_bf16 v[38:41], v[192:195], v[176:179], v[38:41]
	v_mfma_f32_16x16x32_bf16 v[34:37], v[192:195], v[180:183], v[34:37]
	v_mfma_f32_16x16x32_bf16 v[30:33], v[196:199], v[146:149], v[30:33]
	v_mfma_f32_16x16x32_bf16 v[26:29], v[196:199], v[152:155], v[26:29]
	v_mfma_f32_16x16x32_bf16 v[22:25], v[196:199], v[156:159], v[22:25]
	v_mfma_f32_16x16x32_bf16 v[18:21], v[196:199], v[162:165], v[18:21]
	v_mfma_f32_16x16x32_bf16 v[14:17], v[196:199], v[166:169], v[14:17]
	v_mfma_f32_16x16x32_bf16 v[10:13], v[196:199], v[170:173], v[10:13]
	v_mfma_f32_16x16x32_bf16 v[6:9], v[196:199], v[176:179], v[6:9]
	v_mfma_f32_16x16x32_bf16 v[2:5], v[196:199], v[180:183], v[2:5]
	s_setprio 0
	s_mov_b32 s39, s38
	s_add_i32 s38, s38, 0x6000
	s_cmp_eq_u32 s38, 0x12000
	s_cselect_b32 s38, 0, s38
	s_nop 0
	.p2align 3
	s_waitcnt lgkmcnt(0)
; DEVI unsigned pack2(float a, float b) { return __builtin_bit_cast(unsigned, __builtin_convertvector((f32x2_t){a, b}, bf16x2_t)); }
; DEVI float blo(unsigned u) { return __uint_as_float(u << 16); }
; DEVI float bhi(unsigned u) { return __uint_as_float(u & 0xffff0000u); }
; DEVI float siluf_(float x) { return x * __builtin_amdgcn_rcpf(1.f + __expf(-x)); }
;     ...
; #pragma unroll
;   for (int mf = 0; mf < 8; mf++) {
;     const int row = m0 + wm * 128 + mf * 16 + r16;
;     if (EPI == EPI_SWIGLU) {
; #pragma unroll
;       for (int nf = 0; nf < 2; nf++) {
;         const int hcol = (n0 >> 1) + wn * 32 + nf * 16 + quad * 4;
;         f32x4 g = acc[nf][mf], u = acc[nf + 2][mf];
;         u32x2 pk;
;         pk[0] = pack2(siluf_(g[0]) * u[0], siluf_(g[1]) * u[1]);
;         pk[1] = pack2(siluf_(g[2]) * u[2], siluf_(g[3]) * u[3]);
;         *(u32x2*)(outb + (size_t)row * DFF + hcol) = pk;
;       }
;     } else {
; #pragma unroll
;       for (int nf = 0; nf < 4; nf++) {
;         const int col = n0 + wn * 64 + nf * 16 + quad * 4;
;         f32x4 a = acc[nf][mf];
;         if (EPI == EPI_RESID || EPI == EPI_RESID_ATOMIC) {
;           f32x4 x = a;
;           if (EPI == EPI_RESID || kpart == 0) {
;             const u32x2 xr = *(const u32x2*)((const u16*)(p.ws + WS_XB) + (size_t)row * 1024 + col);
;             x[0] += ALPHA * blo(xr[0]); x[1] += ALPHA * bhi(xr[0]); x[2] += ALPHA * blo(xr[1]); x[3] += ALPHA * bhi(xr[1]);
;           }
;           if (EPI == EPI_RESID) *(f32x4*)((float*)(p.ws + WS_XF) + (size_t)row * 1024 + col) = x;
;           else *(f32x4*)((float*)(p.ws + WS_SLAB) + ((size_t)kpart * 512 + (row - T_P)) * 1024 + col) = x;
;         } else {
;           u32x2 pk; pk[0] = pack2(a[0], a[1]); pk[1] = pack2(a[2], a[3]);
;           *(u32x2*)(outb + (size_t)row * ldc + col) = pk;
;         }
	s_nop 0
	v_mfma_f32_16x16x32_bf16 v[126:129], v[232:235], v[200:203], v[126:129]
	v_mfma_f32_16x16x32_bf16 v[122:125], v[232:235], v[204:207], v[122:125]
	v_mfma_f32_16x16x32_bf16 v[118:121], v[232:235], v[208:211], v[118:121]
	v_mfma_f32_16x16x32_bf16 v[114:117], v[232:235], v[212:215], v[114:117]
	v_mfma_f32_16x16x32_bf16 v[110:113], v[232:235], v[216:219], v[110:113]
	v_mfma_f32_16x16x32_bf16 v[106:109], v[232:235], v[220:223], v[106:109]
	v_mfma_f32_16x16x32_bf16 v[102:105], v[232:235], v[224:227], v[102:105]
	v_mfma_f32_16x16x32_bf16 v[98:101], v[232:235], v[228:231], v[98:101]
	v_mfma_f32_16x16x32_bf16 v[94:97], v[236:239], v[200:203], v[94:97]
	v_mfma_f32_16x16x32_bf16 v[90:93], v[236:239], v[204:207], v[90:93]
	v_mfma_f32_16x16x32_bf16 v[86:89], v[236:239], v[208:211], v[86:89]
	v_mfma_f32_16x16x32_bf16 v[82:85], v[236:239], v[212:215], v[82:85]
	v_mfma_f32_16x16x32_bf16 v[78:81], v[236:239], v[216:219], v[78:81]
	v_mfma_f32_16x16x32_bf16 v[74:77], v[236:239], v[220:223], v[74:77]
	v_mfma_f32_16x16x32_bf16 v[70:73], v[236:239], v[224:227], v[70:73]
	v_mfma_f32_16x16x32_bf16 v[66:69], v[236:239], v[228:231], v[66:69]
	v_mfma_f32_16x16x32_bf16 v[62:65], v[240:243], v[200:203], v[62:65]
	v_mfma_f32_16x16x32_bf16 v[58:61], v[240:243], v[204:207], v[58:61]
	v_mfma_f32_16x16x32_bf16 v[54:57], v[240:243], v[208:211], v[54:57]
	v_mfma_f32_16x16x32_bf16 v[50:53], v[240:243], v[212:215], v[50:53]
	v_mfma_f32_16x16x32_bf16 v[46:49], v[240:243], v[216:219], v[46:49]
	v_mfma_f32_16x16x32_bf16 v[42:45], v[240:243], v[220:223], v[42:45]
	v_mfma_f32_16x16x32_bf16 v[38:41], v[240:243], v[224:227], v[38:41]
	v_mfma_f32_16x16x32_bf16 v[34:37], v[240:243], v[228:231], v[34:37]
	v_mfma_f32_16x16x32_bf16 v[30:33], v[244:247], v[200:203], v[30:33]
	v_mfma_f32_16x16x32_bf16 v[26:29], v[244:247], v[204:207], v[26:29]
	v_mfma_f32_16x16x32_bf16 v[22:25], v[244:247], v[208:211], v[22:25]
	v_mfma_f32_16x16x32_bf16 v[18:21], v[244:247], v[212:215], v[18:21]
	v_mfma_f32_16x16x32_bf16 v[14:17], v[244:247], v[216:219], v[14:17]
	v_mfma_f32_16x16x32_bf16 v[10:13], v[244:247], v[220:223], v[10:13]
	v_mfma_f32_16x16x32_bf16 v[6:9], v[244:247], v[224:227], v[6:9]
	v_mfma_f32_16x16x32_bf16 v[2:5], v[244:247], v[228:231], v[2:5]
	s_mov_b32 m0, s41
	s_mov_b32 s8, 0x14000
	s_mov_b32 s9, 0
	s_nop 7
	v_and_b32_e32 v228, 1, v145
	v_cmp_ne_u32_e32 vcc, 0, v228
	v_mov_b32_e32 v229, 0xffffec40
	v_cndmask_b32_e32 v230, 0, v229, vcc
	v_ashrrev_i32_e32 v231, 31, v230
	v_lshl_add_u64 v[140:141], v[140:141], 0, v[230:231]
	v_add_co_u32_e32 v142, vcc, 0x1400, v140
	s_nop 0
	v_addc_co_u32_e32 v143, vcc, 0, v141, vcc
	v_cmp_ne_u32_e32 vcc, 0, v228
	v_cvt_pk_bf16_f32 v126, v126, v127
	v_cvt_pk_bf16_f32 v127, v128, v129
	v_cvt_pk_bf16_f32 v128, v94, v95
	v_cvt_pk_bf16_f32 v129, v96, v97
	v_cvt_pk_bf16_f32 v62, v62, v63
	v_cvt_pk_bf16_f32 v63, v64, v65
	v_cvt_pk_bf16_f32 v64, v30, v31
	v_cvt_pk_bf16_f32 v65, v32, v33
	v_permlane16_swap_b32_e32 v126, v128
	v_permlane16_swap_b32_e32 v127, v129
	v_permlane16_swap_b32_e32 v62, v64
	v_permlane16_swap_b32_e32 v63, v65
	v_mov_b32_dpp v224, v126 quad_perm:[1,0,3,2] row_mask:0xf bank_mask:0xf
	v_mov_b32_dpp v225, v127 quad_perm:[1,0,3,2] row_mask:0xf bank_mask:0xf
	v_mov_b32_dpp v226, v128 quad_perm:[1,0,3,2] row_mask:0xf bank_mask:0xf
	v_mov_b32_dpp v227, v129 quad_perm:[1,0,3,2] row_mask:0xf bank_mask:0xf
	v_mov_b32_dpp v220, v62 quad_perm:[1,0,3,2] row_mask:0xf bank_mask:0xf
	v_mov_b32_dpp v221, v63 quad_perm:[1,0,3,2] row_mask:0xf bank_mask:0xf
	v_mov_b32_dpp v222, v64 quad_perm:[1,0,3,2] row_mask:0xf bank_mask:0xf
	v_mov_b32_dpp v223, v65 quad_perm:[1,0,3,2] row_mask:0xf bank_mask:0xf
	v_cndmask_b32_e32 v62, v224, v62, vcc
	v_cndmask_b32_e32 v63, v225, v63, vcc
	v_cndmask_b32_e32 v64, v226, v64, vcc
	v_cndmask_b32_e32 v65, v227, v65, vcc
	v_cndmask_b32_e32 v126, v126, v220, vcc
	v_cndmask_b32_e32 v127, v127, v221, vcc
	v_cndmask_b32_e32 v128, v128, v222, vcc
	v_cndmask_b32_e32 v129, v129, v223, vcc
	global_store_dwordx4 v[140:141], v[126:129], off
	global_store_dwordx4 v[142:143], v[62:65], off
	v_lshl_add_u64 v[140:141], v[140:141], 0, s[8:9]
	v_lshl_add_u64 v[142:143], v[142:143], 0, s[8:9]
	v_cvt_pk_bf16_f32 v122, v122, v123
	v_cvt_pk_bf16_f32 v123, v124, v125
	v_cvt_pk_bf16_f32 v124, v90, v91
	v_cvt_pk_bf16_f32 v125, v92, v93
	v_cvt_pk_bf16_f32 v58, v58, v59
	v_cvt_pk_bf16_f32 v59, v60, v61
	v_cvt_pk_bf16_f32 v60, v26, v27
	v_cvt_pk_bf16_f32 v61, v28, v29
	v_permlane16_swap_b32_e32 v122, v124
	v_permlane16_swap_b32_e32 v123, v125
	v_permlane16_swap_b32_e32 v58, v60
	v_permlane16_swap_b32_e32 v59, v61
	v_mov_b32_dpp v224, v122 quad_perm:[1,0,3,2] row_mask:0xf bank_mask:0xf
	v_mov_b32_dpp v225, v123 quad_perm:[1,0,3,2] row_mask:0xf bank_mask:0xf
	v_mov_b32_dpp v226, v124 quad_perm:[1,0,3,2] row_mask:0xf bank_mask:0xf
	v_mov_b32_dpp v227, v125 quad_perm:[1,0,3,2] row_mask:0xf bank_mask:0xf
	v_mov_b32_dpp v220, v58 quad_perm:[1,0,3,2] row_mask:0xf bank_mask:0xf
	v_mov_b32_dpp v221, v59 quad_perm:[1,0,3,2] row_mask:0xf bank_mask:0xf
	v_mov_b32_dpp v222, v60 quad_perm:[1,0,3,2] row_mask:0xf bank_mask:0xf
	v_mov_b32_dpp v223, v61 quad_perm:[1,0,3,2] row_mask:0xf bank_mask:0xf
	v_cndmask_b32_e32 v58, v224, v58, vcc
	v_cndmask_b32_e32 v59, v225, v59, vcc
	v_cndmask_b32_e32 v60, v226, v60, vcc
	v_cndmask_b32_e32 v61, v227, v61, vcc
	v_cndmask_b32_e32 v122, v122, v220, vcc
	v_cndmask_b32_e32 v123, v123, v221, vcc
	v_cndmask_b32_e32 v124, v124, v222, vcc
	v_cndmask_b32_e32 v125, v125, v223, vcc
	global_store_dwordx4 v[140:141], v[122:125], off
	global_store_dwordx4 v[142:143], v[58:61], off
	v_lshl_add_u64 v[140:141], v[140:141], 0, s[8:9]
; DEVI unsigned pack2(float a, float b) { return __builtin_bit_cast(unsigned, __builtin_convertvector((f32x2_t){a, b}, bf16x2_t)); }
; DEVI float blo(unsigned u) { return __uint_as_float(u << 16); }
; DEVI float bhi(unsigned u) { return __uint_as_float(u & 0xffff0000u); }
; DEVI float siluf_(float x) { return x * __builtin_amdgcn_rcpf(1.f + __expf(-x)); }
;     ...
; #pragma unroll
;   for (int mf = 0; mf < 8; mf++) {
;     const int row = m0 + wm * 128 + mf * 16 + r16;
;     if (EPI == EPI_SWIGLU) {
; #pragma unroll
;       for (int nf = 0; nf < 2; nf++) {
;         const int hcol = (n0 >> 1) + wn * 32 + nf * 16 + quad * 4;
;         f32x4 g = acc[nf][mf], u = acc[nf + 2][mf];
;         u32x2 pk;
;         pk[0] = pack2(siluf_(g[0]) * u[0], siluf_(g[1]) * u[1]);
;         pk[1] = pack2(siluf_(g[2]) * u[2], siluf_(g[3]) * u[3]);
;         *(u32x2*)(outb + (size_t)row * DFF + hcol) = pk;
;       }
;     } else {
; #pragma unroll
;       for (int nf = 0; nf < 4; nf++) {
;         const int col = n0 + wn * 64 + nf * 16 + quad * 4;
;         f32x4 a = acc[nf][mf];
;         if (EPI == EPI_RESID || EPI == EPI_RESID_ATOMIC) {
;           f32x4 x = a;
;           if (EPI == EPI_RESID || kpart == 0) {
;             const u32x2 xr = *(const u32x2*)((const u16*)(p.ws + WS_XB) + (size_t)row * 1024 + col);
;             x[0] += ALPHA * blo(xr[0]); x[1] += ALPHA * bhi(xr[0]); x[2] += ALPHA * blo(xr[1]); x[3] += ALPHA * bhi(xr[1]);
;           }
;           if (EPI == EPI_RESID) *(f32x4*)((float*)(p.ws + WS_XF) + (size_t)row * 1024 + col) = x;
;           else *(f32x4*)((float*)(p.ws + WS_SLAB) + ((size_t)kpart * 512 + (row - T_P)) * 1024 + col) = x;
;         } else {
;           u32x2 pk; pk[0] = pack2(a[0], a[1]); pk[1] = pack2(a[2], a[3]);
;           *(u32x2*)(outb + (size_t)row * ldc + col) = pk;
;         }
	v_lshl_add_u64 v[142:143], v[142:143], 0, s[8:9]
	v_cvt_pk_bf16_f32 v118, v118, v119
	v_cvt_pk_bf16_f32 v119, v120, v121
	v_cvt_pk_bf16_f32 v120, v86, v87
	v_cvt_pk_bf16_f32 v121, v88, v89
	v_cvt_pk_bf16_f32 v54, v54, v55
	v_cvt_pk_bf16_f32 v55, v56, v57
	v_cvt_pk_bf16_f32 v56, v22, v23
	v_cvt_pk_bf16_f32 v57, v24, v25
	v_permlane16_swap_b32_e32 v118, v120
	v_permlane16_swap_b32_e32 v119, v121
	v_permlane16_swap_b32_e32 v54, v56
	v_permlane16_swap_b32_e32 v55, v57
	v_mov_b32_dpp v224, v118 quad_perm:[1,0,3,2] row_mask:0xf bank_mask:0xf
	v_mov_b32_dpp v225, v119 quad_perm:[1,0,3,2] row_mask:0xf bank_mask:0xf
	v_mov_b32_dpp v226, v120 quad_perm:[1,0,3,2] row_mask:0xf bank_mask:0xf
	v_mov_b32_dpp v227, v121 quad_perm:[1,0,3,2] row_mask:0xf bank_mask:0xf
	v_mov_b32_dpp v220, v54 quad_perm:[1,0,3,2] row_mask:0xf bank_mask:0xf
	v_mov_b32_dpp v221, v55 quad_perm:[1,0,3,2] row_mask:0xf bank_mask:0xf
	v_mov_b32_dpp v222, v56 quad_perm:[1,0,3,2] row_mask:0xf bank_mask:0xf
	v_mov_b32_dpp v223, v57 quad_perm:[1,0,3,2] row_mask:0xf bank_mask:0xf
	v_cndmask_b32_e32 v54, v224, v54, vcc
	v_cndmask_b32_e32 v55, v225, v55, vcc
	v_cndmask_b32_e32 v56, v226, v56, vcc
	v_cndmask_b32_e32 v57, v227, v57, vcc
	v_cndmask_b32_e32 v118, v118, v220, vcc
	v_cndmask_b32_e32 v119, v119, v221, vcc
	v_cndmask_b32_e32 v120, v120, v222, vcc
	v_cndmask_b32_e32 v121, v121, v223, vcc
	global_store_dwordx4 v[140:141], v[118:121], off
	global_store_dwordx4 v[142:143], v[54:57], off
	v_lshl_add_u64 v[140:141], v[140:141], 0, s[8:9]
	v_lshl_add_u64 v[142:143], v[142:143], 0, s[8:9]
	v_cvt_pk_bf16_f32 v114, v114, v115
	v_cvt_pk_bf16_f32 v115, v116, v117
	v_cvt_pk_bf16_f32 v116, v82, v83
	v_cvt_pk_bf16_f32 v117, v84, v85
	v_cvt_pk_bf16_f32 v50, v50, v51
	v_cvt_pk_bf16_f32 v51, v52, v53
	v_cvt_pk_bf16_f32 v52, v18, v19
	v_cvt_pk_bf16_f32 v53, v20, v21
	v_permlane16_swap_b32_e32 v114, v116
	v_permlane16_swap_b32_e32 v115, v117
	v_permlane16_swap_b32_e32 v50, v52
	v_permlane16_swap_b32_e32 v51, v53
	v_mov_b32_dpp v224, v114 quad_perm:[1,0,3,2] row_mask:0xf bank_mask:0xf
	v_mov_b32_dpp v225, v115 quad_perm:[1,0,3,2] row_mask:0xf bank_mask:0xf
	v_mov_b32_dpp v226, v116 quad_perm:[1,0,3,2] row_mask:0xf bank_mask:0xf
	v_mov_b32_dpp v227, v117 quad_perm:[1,0,3,2] row_mask:0xf bank_mask:0xf
	v_mov_b32_dpp v220, v50 quad_perm:[1,0,3,2] row_mask:0xf bank_mask:0xf
	v_mov_b32_dpp v221, v51 quad_perm:[1,0,3,2] row_mask:0xf bank_mask:0xf
	v_mov_b32_dpp v222, v52 quad_perm:[1,0,3,2] row_mask:0xf bank_mask:0xf
	v_mov_b32_dpp v223, v53 quad_perm:[1,0,3,2] row_mask:0xf bank_mask:0xf
	v_cndmask_b32_e32 v50, v224, v50, vcc
	v_cndmask_b32_e32 v51, v225, v51, vcc
	v_cndmask_b32_e32 v52, v226, v52, vcc
	v_cndmask_b32_e32 v53, v227, v53, vcc
	v_cndmask_b32_e32 v114, v114, v220, vcc
	v_cndmask_b32_e32 v115, v115, v221, vcc
	v_cndmask_b32_e32 v116, v116, v222, vcc
	v_cndmask_b32_e32 v117, v117, v223, vcc
	global_store_dwordx4 v[140:141], v[114:117], off
	global_store_dwordx4 v[142:143], v[50:53], off
	v_lshl_add_u64 v[140:141], v[140:141], 0, s[8:9]
	v_lshl_add_u64 v[142:143], v[142:143], 0, s[8:9]
	v_cvt_pk_bf16_f32 v110, v110, v111
	v_cvt_pk_bf16_f32 v111, v112, v113
	v_cvt_pk_bf16_f32 v112, v78, v79
	v_cvt_pk_bf16_f32 v113, v80, v81
	v_cvt_pk_bf16_f32 v46, v46, v47
	v_cvt_pk_bf16_f32 v47, v48, v49
	v_cvt_pk_bf16_f32 v48, v14, v15
	v_cvt_pk_bf16_f32 v49, v16, v17
	v_permlane16_swap_b32_e32 v110, v112
	v_permlane16_swap_b32_e32 v111, v113
	v_permlane16_swap_b32_e32 v46, v48
	v_permlane16_swap_b32_e32 v47, v49
	v_mov_b32_dpp v224, v110 quad_perm:[1,0,3,2] row_mask:0xf bank_mask:0xf
	v_mov_b32_dpp v225, v111 quad_perm:[1,0,3,2] row_mask:0xf bank_mask:0xf
	v_mov_b32_dpp v226, v112 quad_perm:[1,0,3,2] row_mask:0xf bank_mask:0xf
	v_mov_b32_dpp v227, v113 quad_perm:[1,0,3,2] row_mask:0xf bank_mask:0xf
	v_mov_b32_dpp v220, v46 quad_perm:[1,0,3,2] row_mask:0xf bank_mask:0xf
	v_mov_b32_dpp v221, v47 quad_perm:[1,0,3,2] row_mask:0xf bank_mask:0xf
	v_mov_b32_dpp v222, v48 quad_perm:[1,0,3,2] row_mask:0xf bank_mask:0xf
	v_mov_b32_dpp v223, v49 quad_perm:[1,0,3,2] row_mask:0xf bank_mask:0xf
	v_cndmask_b32_e32 v46, v224, v46, vcc
	v_cndmask_b32_e32 v47, v225, v47, vcc
	v_cndmask_b32_e32 v48, v226, v48, vcc
	v_cndmask_b32_e32 v49, v227, v49, vcc
	v_cndmask_b32_e32 v110, v110, v220, vcc
	v_cndmask_b32_e32 v111, v111, v221, vcc
	v_cndmask_b32_e32 v112, v112, v222, vcc
	v_cndmask_b32_e32 v113, v113, v223, vcc
	global_store_dwordx4 v[140:141], v[110:113], off
	global_store_dwordx4 v[142:143], v[46:49], off
; DEVI unsigned pack2(float a, float b) { return __builtin_bit_cast(unsigned, __builtin_convertvector((f32x2_t){a, b}, bf16x2_t)); }
; DEVI float blo(unsigned u) { return __uint_as_float(u << 16); }
; DEVI float bhi(unsigned u) { return __uint_as_float(u & 0xffff0000u); }
; DEVI float siluf_(float x) { return x * __builtin_amdgcn_rcpf(1.f + __expf(-x)); }
;     ...
; #pragma unroll
;   for (int mf = 0; mf < 8; mf++) {
;     const int row = m0 + wm * 128 + mf * 16 + r16;
;     if (EPI == EPI_SWIGLU) {
; #pragma unroll
;       for (int nf = 0; nf < 2; nf++) {
;         const int hcol = (n0 >> 1) + wn * 32 + nf * 16 + quad * 4;
;         f32x4 g = acc[nf][mf], u = acc[nf + 2][mf];
;         u32x2 pk;
;         pk[0] = pack2(siluf_(g[0]) * u[0], siluf_(g[1]) * u[1]);
;         pk[1] = pack2(siluf_(g[2]) * u[2], siluf_(g[3]) * u[3]);
;         *(u32x2*)(outb + (size_t)row * DFF + hcol) = pk;
;       }
;     } else {
; #pragma unroll
;       for (int nf = 0; nf < 4; nf++) {
;         const int col = n0 + wn * 64 + nf * 16 + quad * 4;
;         f32x4 a = acc[nf][mf];
;         if (EPI == EPI_RESID || EPI == EPI_RESID_ATOMIC) {
;           f32x4 x = a;
;           if (EPI == EPI_RESID || kpart == 0) {
;             const u32x2 xr = *(const u32x2*)((const u16*)(p.ws + WS_XB) + (size_t)row * 1024 + col);
;             x[0] += ALPHA * blo(xr[0]); x[1] += ALPHA * bhi(xr[0]); x[2] += ALPHA * blo(xr[1]); x[3] += ALPHA * bhi(xr[1]);
;           }
;           if (EPI == EPI_RESID) *(f32x4*)((float*)(p.ws + WS_XF) + (size_t)row * 1024 + col) = x;
;           else *(f32x4*)((float*)(p.ws + WS_SLAB) + ((size_t)kpart * 512 + (row - T_P)) * 1024 + col) = x;
;         } else {
;           u32x2 pk; pk[0] = pack2(a[0], a[1]); pk[1] = pack2(a[2], a[3]);
;           *(u32x2*)(outb + (size_t)row * ldc + col) = pk;
;         }
	v_lshl_add_u64 v[140:141], v[140:141], 0, s[8:9]
	v_lshl_add_u64 v[142:143], v[142:143], 0, s[8:9]
	v_cvt_pk_bf16_f32 v106, v106, v107
	v_cvt_pk_bf16_f32 v107, v108, v109
	v_cvt_pk_bf16_f32 v108, v74, v75
	v_cvt_pk_bf16_f32 v109, v76, v77
	v_cvt_pk_bf16_f32 v42, v42, v43
	v_cvt_pk_bf16_f32 v43, v44, v45
	v_cvt_pk_bf16_f32 v44, v10, v11
	v_cvt_pk_bf16_f32 v45, v12, v13
	v_permlane16_swap_b32_e32 v106, v108
	v_permlane16_swap_b32_e32 v107, v109
	v_permlane16_swap_b32_e32 v42, v44
	v_permlane16_swap_b32_e32 v43, v45
	v_mov_b32_dpp v224, v106 quad_perm:[1,0,3,2] row_mask:0xf bank_mask:0xf
	v_mov_b32_dpp v225, v107 quad_perm:[1,0,3,2] row_mask:0xf bank_mask:0xf
	v_mov_b32_dpp v226, v108 quad_perm:[1,0,3,2] row_mask:0xf bank_mask:0xf
	v_mov_b32_dpp v227, v109 quad_perm:[1,0,3,2] row_mask:0xf bank_mask:0xf
	v_mov_b32_dpp v220, v42 quad_perm:[1,0,3,2] row_mask:0xf bank_mask:0xf
	v_mov_b32_dpp v221, v43 quad_perm:[1,0,3,2] row_mask:0xf bank_mask:0xf
	v_mov_b32_dpp v222, v44 quad_perm:[1,0,3,2] row_mask:0xf bank_mask:0xf
	v_mov_b32_dpp v223, v45 quad_perm:[1,0,3,2] row_mask:0xf bank_mask:0xf
	v_cndmask_b32_e32 v42, v224, v42, vcc
	v_cndmask_b32_e32 v43, v225, v43, vcc
	v_cndmask_b32_e32 v44, v226, v44, vcc
	v_cndmask_b32_e32 v45, v227, v45, vcc
	v_cndmask_b32_e32 v106, v106, v220, vcc
	v_cndmask_b32_e32 v107, v107, v221, vcc
	v_cndmask_b32_e32 v108, v108, v222, vcc
	v_cndmask_b32_e32 v109, v109, v223, vcc
	global_store_dwordx4 v[140:141], v[106:109], off
	global_store_dwordx4 v[142:143], v[42:45], off
	v_lshl_add_u64 v[140:141], v[140:141], 0, s[8:9]
	v_lshl_add_u64 v[142:143], v[142:143], 0, s[8:9]
	v_cvt_pk_bf16_f32 v102, v102, v103
	v_cvt_pk_bf16_f32 v103, v104, v105
	v_cvt_pk_bf16_f32 v104, v70, v71
	v_cvt_pk_bf16_f32 v105, v72, v73
	v_cvt_pk_bf16_f32 v38, v38, v39
	v_cvt_pk_bf16_f32 v39, v40, v41
	v_cvt_pk_bf16_f32 v40, v6, v7
	v_cvt_pk_bf16_f32 v41, v8, v9
	v_permlane16_swap_b32_e32 v102, v104
	v_permlane16_swap_b32_e32 v103, v105
	v_permlane16_swap_b32_e32 v38, v40
	v_permlane16_swap_b32_e32 v39, v41
	v_mov_b32_dpp v224, v102 quad_perm:[1,0,3,2] row_mask:0xf bank_mask:0xf
	v_mov_b32_dpp v225, v103 quad_perm:[1,0,3,2] row_mask:0xf bank_mask:0xf
	v_mov_b32_dpp v226, v104 quad_perm:[1,0,3,2] row_mask:0xf bank_mask:0xf
	v_mov_b32_dpp v227, v105 quad_perm:[1,0,3,2] row_mask:0xf bank_mask:0xf
	v_mov_b32_dpp v220, v38 quad_perm:[1,0,3,2] row_mask:0xf bank_mask:0xf
	v_mov_b32_dpp v221, v39 quad_perm:[1,0,3,2] row_mask:0xf bank_mask:0xf
	v_mov_b32_dpp v222, v40 quad_perm:[1,0,3,2] row_mask:0xf bank_mask:0xf
	v_mov_b32_dpp v223, v41 quad_perm:[1,0,3,2] row_mask:0xf bank_mask:0xf
	v_cndmask_b32_e32 v38, v224, v38, vcc
	v_cndmask_b32_e32 v39, v225, v39, vcc
	v_cndmask_b32_e32 v40, v226, v40, vcc
	v_cndmask_b32_e32 v41, v227, v41, vcc
	v_cndmask_b32_e32 v102, v102, v220, vcc
	v_cndmask_b32_e32 v103, v103, v221, vcc
	v_cndmask_b32_e32 v104, v104, v222, vcc
	v_cndmask_b32_e32 v105, v105, v223, vcc
	global_store_dwordx4 v[140:141], v[102:105], off
	global_store_dwordx4 v[142:143], v[38:41], off
	v_lshl_add_u64 v[140:141], v[140:141], 0, s[8:9]
	v_lshl_add_u64 v[142:143], v[142:143], 0, s[8:9]
	v_cvt_pk_bf16_f32 v98, v98, v99
	v_cvt_pk_bf16_f32 v99, v100, v101
	v_cvt_pk_bf16_f32 v100, v66, v67
	v_cvt_pk_bf16_f32 v101, v68, v69
	v_cvt_pk_bf16_f32 v34, v34, v35
	v_cvt_pk_bf16_f32 v35, v36, v37
	v_cvt_pk_bf16_f32 v36, v2, v3
	v_cvt_pk_bf16_f32 v37, v4, v5
	v_permlane16_swap_b32_e32 v98, v100
	v_permlane16_swap_b32_e32 v99, v101
	v_permlane16_swap_b32_e32 v34, v36
	v_permlane16_swap_b32_e32 v35, v37
	v_mov_b32_dpp v224, v98 quad_perm:[1,0,3,2] row_mask:0xf bank_mask:0xf
	v_mov_b32_dpp v225, v99 quad_perm:[1,0,3,2] row_mask:0xf bank_mask:0xf
	v_mov_b32_dpp v226, v100 quad_perm:[1,0,3,2] row_mask:0xf bank_mask:0xf
	v_mov_b32_dpp v227, v101 quad_perm:[1,0,3,2] row_mask:0xf bank_mask:0xf
	v_mov_b32_dpp v220, v34 quad_perm:[1,0,3,2] row_mask:0xf bank_mask:0xf
	v_mov_b32_dpp v221, v35 quad_perm:[1,0,3,2] row_mask:0xf bank_mask:0xf
	v_mov_b32_dpp v222, v36 quad_perm:[1,0,3,2] row_mask:0xf bank_mask:0xf
	v_mov_b32_dpp v223, v37 quad_perm:[1,0,3,2] row_mask:0xf bank_mask:0xf
	v_cndmask_b32_e32 v34, v224, v34, vcc
	v_cndmask_b32_e32 v35, v225, v35, vcc
	v_cndmask_b32_e32 v36, v226, v36, vcc
	v_cndmask_b32_e32 v37, v227, v37, vcc
	v_cndmask_b32_e32 v98, v98, v220, vcc
	v_cndmask_b32_e32 v99, v99, v221, vcc
	v_cndmask_b32_e32 v100, v100, v222, vcc
	v_cndmask_b32_e32 v101, v101, v223, vcc
	global_store_dwordx4 v[140:141], v[98:101], off
	global_store_dwordx4 v[142:143], v[34:37], off
	s_branch .LBB0_886
